# L2 software prefetch (dummy loads) of the LRU unit's 32 activation rows at unit start, hides the second remote-load latency
# speedup vs baseline: 1.0016x; 1.0016x over previous
; #define LAS __attribute__((address_space(3)))
; template <int MODE>
; __device__ __forceinline__ void lru_unit(const Args& a, int l, int b, int ch, LAS unsigned char* lds) {
;     int tid_ = threadIdx.x; asm volatile("" : "+v"(tid_));
;     const int tid = tid_, w = __builtin_amdgcn_readfirstlane(tid >> 6), lane = tid & 63, r32 = lane & 31, h = lane >> 5;
;     const int c = w * 64 + lane, t0 = ch * 32;
;     const bf16* proj = (const bf16*)(a.ws + WS_PROJ);
;     LAS unsigned char* xcb = lds + w * 12800;
;     LAS float* au = (LAS float*)(lds + w * 12800 + 4608);
;     const float* cw = a.in[7] + (size_t)l * 4 * LW;
;     const float cw0 = cw[c], cw1 = cw[LW + c], cw2 = cw[2 * LW + c], cw3 = cw[3 * LW + c], cb = a.in[8][l * LW + c];
;     float prm[2][2][3];
; #pragma unroll
;     for (int d = 0; d < 2; ++d)
; #pragma unroll
;         for (int nt = 0; nt < 2; ++nt) { const int cc = (l * 2 + d) * LW + w * 64 + nt * 32 + r32;
;             prm[d][nt][0] = a.in[10][cc]; prm[d][nt][1] = a.in[12][cc]; prm[d][nt][2] = a.in[13][cc]; }
;     const bf16* xp = proj + (size_t)b * SEQ * DIN + c;
;     float xin[35], gl[32];
;     unsigned short xraw[35], graw[32];
; #pragma unroll
;     for (int i = 0; i < 35; ++i) { const int t = t0 - 2 + i, tc = t < 0 ? 0 : (t >= SEQ ? SEQ - 1 : t); xraw[i] = xp[(size_t)tc * DIN]; }
; __global__ void __launch_bounds__(NTHR, 2) mega_fwd(Args a) {
;     ...
;                 for (int u = bx; u < 256 + NB * NCH; u += G) {
;                     __syncthreads();
;                     if (u < 256) { _Pragma("unroll 1") for (int rp = 0; rp < PROBE_ATTNREP; ++rp) { attn_unit(a, l, u >> 6, u & 63, lds); __syncthreads(); } }
;                     else { const int v = u - 256; _Pragma("unroll 1") for (int rp = 0; rp < PROBE_D1REP; ++rp) lru_unit<0>(a, l, v / NCH, v % NCH, lds); }
.LBB0_180:
	s_cmpk_gt_i32 s65, 0xff
	s_mov_b64 s[0:1], -1
	s_barrier
	s_cbranch_scc0 .LBB0_182
	s_add_i32 s0, s65, 0xffffff00
	s_lshr_b32 s40, s0, 7
	s_mul_i32 s88, s40, 0x700000
	s_and_b32 s28, s65, 0x7f
	s_lshl_b32 s29, s28, 5
	s_lshl_b64 s[0:1], s[88:89], 1
	s_add_u32 s38, s24, s0
	s_addc_u32 s39, s25, s1
	s_lshl_b32 s0, s40, 21
	s_lshl_b32 s1, s28, 14
	s_or_b32 s88, s0, s1
	s_min_u32 s41, s29, 0xfdf
	s_lshl_b64 s[0:1], s[88:89], 2
	s_add_u32 s44, s72, s0
	s_addc_u32 s45, s73, s1
	s_add_u32 s46, s50, s0
	s_addc_u32 s47, s51, s1
	s_lshl_b32 s0, s40, 17
	s_lshl_b32 s1, s28, 10
	s_or_b32 s88, s0, s1
	s_lshl_b64 s[0:1], s[88:89], 3
	s_add_u32 s42, s74, s0
	s_addc_u32 s43, s75, s1
	v_mov_b32_e32 v66, v226
	s_add_u32 s40, s50, s0
	s_movk_i32 s59, 0xffc0
	v_readfirstlane_b32 s0, v66
	s_mul_i32 s88, s28, 0x1c000
	s_mov_b32 s4, 0x1c000
	v_mov_b32_e32 v0, s0
	v_bfi_b32 v82, s59, v0, v66
	v_ashrrev_i32_e32 v83, 31, v82
	v_lshl_add_u64 v[36:37], v[82:83], 1, s[38:39]
	v_lshl_add_u64 v[4:5], v[36:37], 0, s[88:89]
	v_mov_b32_e32 v214, 0x1c00
	v_mov_b32_e32 v215, 0
	v_mov_b32_e32 v212, v4
	v_mov_b32_e32 v213, v5
	global_load_ushort v210, v[212:213], off
	global_load_ushort v210, v[212:213], off offset:3584
	v_lshl_add_u64 v[212:213], v[212:213], 0, v[214:215]
	global_load_ushort v210, v[212:213], off
	global_load_ushort v210, v[212:213], off offset:3584
	v_lshl_add_u64 v[212:213], v[212:213], 0, v[214:215]
	global_load_ushort v210, v[212:213], off
	global_load_ushort v210, v[212:213], off offset:3584
	v_lshl_add_u64 v[212:213], v[212:213], 0, v[214:215]
	global_load_ushort v210, v[212:213], off
	global_load_ushort v210, v[212:213], off offset:3584
	v_lshl_add_u64 v[212:213], v[212:213], 0, v[214:215]
	global_load_ushort v210, v[212:213], off
	global_load_ushort v210, v[212:213], off offset:3584
	v_lshl_add_u64 v[212:213], v[212:213], 0, v[214:215]
	global_load_ushort v210, v[212:213], off
	global_load_ushort v210, v[212:213], off offset:3584
	v_lshl_add_u64 v[212:213], v[212:213], 0, v[214:215]
	global_load_ushort v210, v[212:213], off
	global_load_ushort v210, v[212:213], off offset:3584
	v_lshl_add_u64 v[212:213], v[212:213], 0, v[214:215]
	global_load_ushort v210, v[212:213], off
	global_load_ushort v210, v[212:213], off offset:3584
	v_lshl_add_u64 v[212:213], v[212:213], 0, v[214:215]
	global_load_ushort v210, v[212:213], off
	global_load_ushort v210, v[212:213], off offset:3584
	v_lshl_add_u64 v[212:213], v[212:213], 0, v[214:215]
	global_load_ushort v210, v[212:213], off
	global_load_ushort v210, v[212:213], off offset:3584
	v_lshl_add_u64 v[212:213], v[212:213], 0, v[214:215]
	global_load_ushort v210, v[212:213], off
	global_load_ushort v210, v[212:213], off offset:3584
	v_lshl_add_u64 v[212:213], v[212:213], 0, v[214:215]
	global_load_ushort v210, v[212:213], off
	global_load_ushort v210, v[212:213], off offset:3584
	v_lshl_add_u64 v[212:213], v[212:213], 0, v[214:215]
	global_load_ushort v210, v[212:213], off
	global_load_ushort v210, v[212:213], off offset:3584
	v_lshl_add_u64 v[212:213], v[212:213], 0, v[214:215]
	global_load_ushort v210, v[212:213], off
	global_load_ushort v210, v[212:213], off offset:3584
	v_lshl_add_u64 v[212:213], v[212:213], 0, v[214:215]
	global_load_ushort v210, v[212:213], off
	global_load_ushort v210, v[212:213], off offset:3584
	v_lshl_add_u64 v[212:213], v[212:213], 0, v[214:215]
	global_load_ushort v210, v[212:213], off
	global_load_ushort v210, v[212:213], off offset:3584
	v_lshl_add_u64 v[212:213], v[212:213], 0, v[214:215]
	s_mul_i32 s88, s41, 0xe00
	v_lshl_add_u64 v[2:3], v[36:37], 0, s[88:89]
	v_add_co_u32_e32 v2, vcc, s4, v2
	v_readlane_b32 s4, v254, 37
	s_nop 0
	v_addc_co_u32_e32 v3, vcc, 0, v3, vcc
	global_load_ushort v0, v[2:3], off
	v_lshlrev_b64 v[2:3], 2, v[82:83]
	v_readlane_b32 s5, v254, 38
	s_movk_i32 s61, 0x1000
	s_movk_i32 s59, 0x2000
	v_lshl_add_u64 v[24:25], s[4:5], 0, v[2:3]
	v_add_co_u32_e32 v26, vcc, s61, v24
	s_movk_i32 s60, 0x3000
	s_nop 0
	v_addc_co_u32_e32 v27, vcc, 0, v25, vcc
	v_add_co_u32_e32 v30, vcc, s61, v4
	s_addc_u32 s41, s51, s1
	s_nop 0
	v_addc_co_u32_e32 v31, vcc, 0, v5, vcc
	v_add_co_u32_e32 v28, vcc, s59, v4
	s_movk_i32 s1, 0x4000
	s_nop 0
	v_addc_co_u32_e32 v29, vcc, 0, v5, vcc
	v_add_co_u32_e32 v32, vcc, s60, v4
	v_and_b32_e32 v164, 31, v66
	s_nop 0
	v_addc_co_u32_e32 v33, vcc, 0, v5, vcc
	v_add_co_u32_e32 v22, vcc, s1, v4
	s_movk_i32 s1, 0x5000
	s_nop 0
	v_addc_co_u32_e32 v23, vcc, 0, v5, vcc
	v_add_co_u32_e32 v10, vcc, s1, v4
	s_movk_i32 s1, 0x6000
	s_nop 0
	v_addc_co_u32_e32 v11, vcc, 0, v5, vcc
	v_add_co_u32_e32 v20, vcc, s1, v4
	s_movk_i32 s1, 0x7000
	s_nop 0
	v_addc_co_u32_e32 v21, vcc, 0, v5, vcc
	v_add_co_u32_e32 v18, vcc, s1, v4
	s_mov_b32 s1, 0x8000
	s_nop 0
	v_addc_co_u32_e32 v19, vcc, 0, v5, vcc
	v_add_co_u32_e32 v12, vcc, s1, v4
	s_mov_b32 s1, 0x9000
	s_nop 0
	v_addc_co_u32_e32 v13, vcc, 0, v5, vcc
	v_add_co_u32_e32 v14, vcc, s1, v4
	s_mov_b32 s1, 0xa000
	s_nop 0
	v_addc_co_u32_e32 v15, vcc, 0, v5, vcc
	v_add_co_u32_e32 v16, vcc, s1, v4
	s_mov_b32 s1, 0xc000
	s_nop 0
	v_addc_co_u32_e32 v17, vcc, 0, v5, vcc
	v_add_co_u32_e32 v6, vcc, s90, v4
	v_readlane_b32 s4, v254, 39
	s_nop 0
	v_addc_co_u32_e32 v7, vcc, 0, v5, vcc
	v_add_co_u32_e32 v8, vcc, s1, v4
	s_and_b32 s1, s0, 0xffffffc0
	s_nop 0
	v_addc_co_u32_e32 v9, vcc, 0, v5, vcc
	s_cmpk_lg_i32 s28, 0x7f
	s_cselect_b64 vcc, -1, 0
	s_add_i32 s28, s29, -2
	s_max_i32 s38, s28, 0
	s_add_i32 s29, s29, -1
	s_mul_i32 s88, s38, 0xe00
	s_max_i32 s38, s29, 0
	v_lshl_add_u64 v[34:35], v[36:37], 0, s[88:89]
	s_mul_i32 s88, s38, 0xe00
	v_lshl_add_u64 v[36:37], v[36:37], 0, s[88:89]
	global_load_ushort v64, v[36:37], off
	global_load_ushort v67, v[32:33], off offset:2048
	global_load_ushort v85, v[30:31], off offset:3072
	global_load_ushort v65, v[34:35], off
	v_or_b32_e32 v30, s4, v164
	v_add_u32_e32 v30, s1, v30
	v_ashrrev_i32_e32 v31, 31, v30
	v_readlane_b32 s4, v252, 16
	v_lshlrev_b64 v[32:33], 2, v[30:31]
	v_readlane_b32 s14, v252, 26
	v_readlane_b32 s15, v252, 27
	s_waitcnt vmcnt(4)
; template <int MODE>
; __device__ __forceinline__ void lru_unit(const Args& a, int l, int b, int ch, LAS unsigned char* lds) {
;     ...
;     const float cw0 = cw[c], cw1 = cw[LW + c], cw2 = cw[2 * LW + c], cw3 = cw[3 * LW + c], cb = a.in[8][l * LW + c];
;     float prm[2][2][3];
; #pragma unroll
;     for (int d = 0; d < 2; ++d)
; #pragma unroll
;         for (int nt = 0; nt < 2; ++nt) { const int cc = (l * 2 + d) * LW + w * 64 + nt * 32 + r32;
;             prm[d][nt][0] = a.in[10][cc]; prm[d][nt][1] = a.in[12][cc]; prm[d][nt][2] = a.in[13][cc]; }
;     ...
;         for (int nt = 0; nt < 2; ++nt) { prm[d][nt][0] *= -1.4426950408889634f; prm[d][nt][1] *= -1.4426950408889634f;
;             prm[d][nt][2] = -8.f * 1.4426950408889634f * log1pf(__expf(-prm[d][nt][2])); }
	v_lshlrev_b32_e32 v0, 16, v0
	s_mov_b32 s1, 0xd000
	v_lshl_add_u64 v[68:69], s[14:15], 0, v[32:33]
	global_load_dword v30, v[68:69], off
	global_load_ushort v87, v[4:5], off offset:3584
	v_cndmask_b32_e32 v31, 0, v0, vcc
	v_add_co_u32_e32 v34, vcc, s1, v4
	s_mov_b32 s1, 0xe000
	s_nop 0
	v_addc_co_u32_e32 v35, vcc, 0, v5, vcc
	v_add_co_u32_e32 v36, vcc, s1, v4
	s_mov_b32 s1, 0xf000
	s_nop 0
	v_addc_co_u32_e32 v37, vcc, 0, v5, vcc
	v_add_co_u32_e32 v38, vcc, s1, v4
	s_mov_b32 s1, 0x11000
	s_nop 0
	v_addc_co_u32_e32 v39, vcc, 0, v5, vcc
	v_add_co_u32_e32 v40, vcc, s70, v4
	global_load_dword v84, v[68:69], off offset:128
	global_load_dword v88, v[68:69], off offset:2048
	global_load_dword v86, v[68:69], off offset:2176
	v_addc_co_u32_e32 v41, vcc, 0, v5, vcc
	v_add_co_u32_e32 v42, vcc, s1, v4
	s_mov_b32 s1, 0x12000
	s_nop 0
	v_addc_co_u32_e32 v43, vcc, 0, v5, vcc
	v_add_co_u32_e32 v44, vcc, s1, v4
	s_mov_b32 s1, 0x13000
	s_nop 0
	v_addc_co_u32_e32 v45, vcc, 0, v5, vcc
	v_add_co_u32_e32 v46, vcc, s1, v4
	s_mov_b32 s1, 0x14000
	s_nop 0
	v_addc_co_u32_e32 v47, vcc, 0, v5, vcc
	v_add_co_u32_e32 v48, vcc, s1, v4
	s_mov_b32 s1, 0x15000
	s_nop 0
	v_addc_co_u32_e32 v49, vcc, 0, v5, vcc
	v_add_co_u32_e32 v50, vcc, s1, v4
	s_mov_b32 s1, 0x17000
	s_nop 0
	v_addc_co_u32_e32 v51, vcc, 0, v5, vcc
	v_add_co_u32_e32 v52, vcc, s71, v4
	v_readlane_b32 s6, v252, 18
	s_nop 0
	v_addc_co_u32_e32 v53, vcc, 0, v5, vcc
	v_add_co_u32_e32 v54, vcc, s1, v4
	s_mov_b32 s1, 0x18000
	s_nop 0
	v_addc_co_u32_e32 v55, vcc, 0, v5, vcc
	v_add_co_u32_e32 v56, vcc, s1, v4
	s_mov_b32 s1, 0x19000
	s_nop 0
	v_addc_co_u32_e32 v57, vcc, 0, v5, vcc
	v_add_co_u32_e32 v58, vcc, s1, v4
	s_mov_b32 s1, 0x1b000
	s_nop 0
	v_addc_co_u32_e32 v59, vcc, 0, v5, vcc
	v_add_co_u32_e32 v60, vcc, s1, v4
	s_mov_b32 s1, 0x1a000
	s_nop 0
	v_addc_co_u32_e32 v61, vcc, 0, v5, vcc
	v_add_co_u32_e32 v62, vcc, s1, v4
	s_ashr_i32 s1, s0, 6
	s_mul_i32 s0, s1, 0x3200
	s_add_i32 s0, s0, 0
	v_addc_co_u32_e32 v63, vcc, 0, v5, vcc
	s_waitcnt vmcnt(4)
	v_mul_f32_e32 v30, 0xbfb8aa3b, v30
	v_exp_f32_e32 v30, v30
	s_cmpk_lt_u32 s28, 0x1000
	s_cselect_b64 vcc, -1, 0
	s_cmpk_lt_u32 s29, 0x1000
	v_lshlrev_b32_e32 v0, 16, v65
	v_lshlrev_b32_e32 v64, 16, v64
	s_cselect_b64 s[38:39], -1, 0
	v_cndmask_b32_e64 v65, 0, v64, s[38:39]
	v_cndmask_b32_e32 v64, 0, v0, vcc
	v_add_f32_e32 v0, 1.0, v30
	v_frexp_mant_f32_e32 v70, v0
	v_cvt_f64_f32_e32 v[68:69], v0
	s_mov_b32 s6, 0x3f2aaaab
	v_frexp_exp_i32_f64_e32 v68, v[68:69]
	v_cmp_gt_f32_e32 vcc, s6, v70
	v_readlane_b32 s7, v252, 19
	s_mov_b32 s7, 0x3f317218
	v_subbrev_co_u32_e32 v76, vcc, 0, v68, vcc
	v_add_f32_e32 v68, -1.0, v0
	v_sub_f32_e32 v69, v68, v0
	v_add_f32_e32 v69, 1.0, v69
	v_sub_f32_e32 v68, v30, v68
	v_add_f32_e32 v68, v68, v69
	v_sub_u32_e32 v69, 0, v76
	v_ldexp_f32 v0, v0, v69
	v_add_f32_e32 v70, -1.0, v0
	v_ldexp_f32 v68, v68, v69
	v_add_f32_e32 v69, 1.0, v70
	v_sub_f32_e32 v69, v0, v69
	v_add_f32_e32 v71, v68, v69
	v_add_f32_e32 v69, 1.0, v0
	v_add_f32_e32 v72, -1.0, v69
	v_sub_f32_e32 v0, v0, v72
	v_add_f32_e32 v0, v68, v0
	v_add_f32_e32 v77, v69, v0
	v_rcp_f32_e32 v78, v77
	v_sub_f32_e32 v68, v77, v69
	v_add_f32_e32 v69, v70, v71
	v_sub_f32_e32 v0, v0, v68
	v_mul_f32_e32 v80, v69, v78
	v_sub_f32_e32 v68, v69, v70
	v_mul_f32_e32 v70, v77, v80
	v_fma_f32 v72, v80, v77, -v70
	v_fmac_f32_e32 v72, v80, v0
	v_sub_f32_e32 v79, v71, v68
	v_add_f32_e32 v68, v70, v72
	v_sub_f32_e32 v71, v69, v68
	v_pk_add_f32 v[74:75], v[68:69], v[70:71] neg_lo:[0,1] neg_hi:[0,1]
	v_mov_b32_e32 v73, v68
	v_pk_add_f32 v[68:69], v[74:75], v[72:73] neg_lo:[0,1] neg_hi:[0,1]
	v_readlane_b32 s10, v252, 22
	v_add_f32_e32 v69, v79, v69
	v_add_f32_e32 v68, v68, v69
	v_add_f32_e32 v69, v71, v68
	v_mul_f32_e32 v79, v78, v69
	v_mul_f32_e32 v70, v77, v79
	v_fma_f32 v72, v79, v77, -v70
	v_fmac_f32_e32 v72, v79, v0
	v_sub_f32_e32 v0, v71, v69
	v_add_f32_e32 v0, v68, v0
	v_add_f32_e32 v68, v70, v72
	v_sub_f32_e32 v71, v69, v68
	v_pk_add_f32 v[74:75], v[68:69], v[70:71] neg_lo:[0,1] neg_hi:[0,1]
	v_mov_b32_e32 v73, v68
	v_pk_add_f32 v[68:69], v[74:75], v[72:73] neg_lo:[0,1] neg_hi:[0,1]
	s_mov_b32 s10, 0x7f800000
	v_add_f32_e32 v0, v0, v69
	v_add_f32_e32 v0, v68, v0
	v_add_f32_e32 v69, v80, v79
	v_add_f32_e32 v0, v71, v0
	v_sub_f32_e32 v68, v69, v80
	v_mul_f32_e32 v0, v78, v0
	v_sub_f32_e32 v68, v79, v68
	v_add_f32_e32 v0, v68, v0
	v_add_f32_e32 v70, v69, v0
	v_mul_f32_e32 v72, v70, v70
	v_fmamk_f32 v68, v72, 0x3e9b6dac, v231
	v_fmaak_f32 v191, v72, v68, 0x3f2aaada
	v_cvt_f32_i32_e32 v68, v76
	v_sub_f32_e32 v69, v70, v69
	v_sub_f32_e32 v0, v0, v69
	v_mul_f32_e32 v69, v70, v72
	v_pk_mul_f32 v[72:73], v[68:69], v[190:191]
	v_ldexp_f32 v71, v70, 1
	v_fma_f32 v70, v68, s7, -v72
	v_fmac_f32_e32 v70, 0xb102e308, v68
	v_pk_add_f32 v[68:69], v[72:73], v[70:71]
	v_ldexp_f32 v0, v0, 1
	v_sub_f32_e32 v71, v69, v71
	v_sub_f32_e32 v71, v73, v71
	v_add_f32_e32 v75, v0, v71
	v_mov_b32_e32 v74, v72
	v_pk_add_f32 v[72:73], v[68:69], v[72:73] neg_lo:[0,1] neg_hi:[0,1]
	v_pk_add_f32 v[76:77], v[68:69], v[74:75]
	v_mov_b32_e32 v71, v68
	v_mov_b32_e32 v73, v77
	v_pk_add_f32 v[78:79], v[70:71], v[72:73] neg_lo:[0,1] neg_hi:[0,1]
	v_pk_add_f32 v[70:71], v[70:71], v[72:73]
	v_mov_b32_e32 v74, v75
	v_pk_add_f32 v[72:73], v[70:71], v[68:69] op_sel:[1,0] op_sel_hi:[0,1] neg_lo:[0,1] neg_hi:[0,1]
	v_pk_add_f32 v[80:81], v[76:77], v[72:73] op_sel_hi:[1,0] neg_lo:[0,1] neg_hi:[0,1]
	v_mov_b32_e32 v76, v77
	v_mov_b32_e32 v77, v71
	v_pk_mov_b32 v[72:73], v[68:69], v[72:73] op_sel:[1,0]
	v_mov_b32_e32 v75, v68
	v_pk_add_f32 v[72:73], v[76:77], v[72:73] neg_lo:[0,1] neg_hi:[0,1]
	v_mov_b32_e32 v80, v78
	v_pk_add_f32 v[68:69], v[74:75], v[72:73] neg_lo:[0,1] neg_hi:[0,1]
	v_mov_b32_e32 v79, v71
	v_pk_add_f32 v[72:73], v[80:81], v[68:69]
	v_cmp_neq_f32_e32 vcc, s10, v30
	v_pk_add_f32 v[74:75], v[72:73], v[72:73] op_sel:[0,1] op_sel_hi:[1,0]
	v_readlane_b32 s11, v252, 23
	v_pk_add_f32 v[70:71], v[70:71], v[74:75] op_sel:[1,0] op_sel_hi:[0,1]
	v_mov_b32_e32 v73, v70
	v_pk_add_f32 v[76:77], v[72:73], v[78:79] neg_lo:[0,1] neg_hi:[0,1]
	v_mov_b32_e32 v69, v74
	v_sub_f32_e32 v0, v72, v76
	v_pk_add_f32 v[68:69], v[68:69], v[76:77] neg_lo:[0,1] neg_hi:[0,1]
	v_sub_f32_e32 v0, v78, v0
	v_add_f32_e32 v0, v68, v0
	v_add_f32_e32 v0, v0, v69
	s_waitcnt vmcnt(2)
; template <int MODE>
; __device__ __forceinline__ void lru_unit(const Args& a, int l, int b, int ch, LAS unsigned char* lds) {
;     ...
;     for (int i = 0; i < 35; ++i) { const int t = t0 - 2 + i, tc = t < 0 ? 0 : (t >= SEQ ? SEQ - 1 : t); xraw[i] = xp[(size_t)tc * DIN]; }
;     ...
;         for (int nt = 0; nt < 2; ++nt) { prm[d][nt][0] *= -1.4426950408889634f; prm[d][nt][1] *= -1.4426950408889634f;
;             prm[d][nt][2] = -8.f * 1.4426950408889634f * log1pf(__expf(-prm[d][nt][2])); }
	v_mul_f32_e32 v68, 0xbfb8aa3b, v84
	v_add_f32_e32 v0, v70, v0
	v_exp_f32_e32 v84, v68
	v_cndmask_b32_e32 v0, v232, v0, vcc
	v_cmp_ngt_f32_e32 vcc, -1.0, v30
	s_mov_b32 s11, 0x33800000
	s_lshl_b32 s28, s1, 1
	v_cndmask_b32_e32 v0, v233, v0, vcc
	v_cmp_neq_f32_e32 vcc, -1.0, v30
	s_ashr_i32 s29, s28, 31
	s_lshl_b64 s[28:29], s[28:29], 13
	v_cndmask_b32_e32 v0, v234, v0, vcc
	v_cmp_lt_f32_e64 vcc, |v30|, s11
	v_readlane_b32 s1, v254, 40
	s_add_u32 s28, s1, s28
	v_cndmask_b32_e32 v126, v0, v30, vcc
	v_add_f32_e32 v0, 1.0, v84
	v_frexp_mant_f32_e32 v30, v0
	v_cvt_f64_f32_e32 v[68:69], v0
	v_frexp_exp_i32_f64_e32 v68, v[68:69]
	v_cmp_gt_f32_e32 vcc, s6, v30
	v_readlane_b32 s1, v254, 41
	v_bfe_u32 v165, v66, 5, 1
	v_subbrev_co_u32_e32 v30, vcc, 0, v68, vcc
	v_add_f32_e32 v68, -1.0, v0
	v_sub_f32_e32 v69, v68, v0
	v_add_f32_e32 v69, 1.0, v69
	v_sub_f32_e32 v68, v84, v68
	v_add_f32_e32 v68, v68, v69
	v_sub_u32_e32 v69, 0, v30
	v_ldexp_f32 v0, v0, v69
	v_add_f32_e32 v70, -1.0, v0
	v_ldexp_f32 v68, v68, v69
	v_add_f32_e32 v69, 1.0, v70
	v_sub_f32_e32 v69, v0, v69
	v_add_f32_e32 v71, v68, v69
	v_add_f32_e32 v69, 1.0, v0
	v_add_f32_e32 v72, -1.0, v69
	v_sub_f32_e32 v0, v0, v72
	v_add_f32_e32 v0, v68, v0
	v_add_f32_e32 v76, v69, v0
	v_rcp_f32_e32 v77, v76
	v_sub_f32_e32 v68, v76, v69
	v_add_f32_e32 v69, v70, v71
	v_sub_f32_e32 v0, v0, v68
	v_mul_f32_e32 v79, v69, v77
	v_sub_f32_e32 v68, v69, v70
	v_mul_f32_e32 v70, v76, v79
	v_fma_f32 v72, v79, v76, -v70
	v_fmac_f32_e32 v72, v79, v0
	v_sub_f32_e32 v78, v71, v68
	v_add_f32_e32 v68, v70, v72
	v_sub_f32_e32 v71, v69, v68
	v_pk_add_f32 v[74:75], v[68:69], v[70:71] neg_lo:[0,1] neg_hi:[0,1]
	v_mov_b32_e32 v73, v68
	v_pk_add_f32 v[68:69], v[74:75], v[72:73] neg_lo:[0,1] neg_hi:[0,1]
	v_cmp_neq_f32_e32 vcc, s10, v84
	v_add_f32_e32 v69, v78, v69
	v_add_f32_e32 v68, v68, v69
	v_add_f32_e32 v69, v71, v68
	v_mul_f32_e32 v78, v77, v69
	v_mul_f32_e32 v70, v76, v78
	v_fma_f32 v72, v78, v76, -v70
	v_fmac_f32_e32 v72, v78, v0
	v_sub_f32_e32 v0, v71, v69
	v_add_f32_e32 v0, v68, v0
	v_add_f32_e32 v68, v70, v72
	v_sub_f32_e32 v71, v69, v68
	v_pk_add_f32 v[74:75], v[68:69], v[70:71] neg_lo:[0,1] neg_hi:[0,1]
	v_mov_b32_e32 v73, v68
	v_pk_add_f32 v[68:69], v[74:75], v[72:73] neg_lo:[0,1] neg_hi:[0,1]
	s_addc_u32 s29, s1, s29
	v_add_f32_e32 v0, v0, v69
	v_add_f32_e32 v0, v68, v0
	v_add_f32_e32 v69, v79, v78
	v_add_f32_e32 v0, v71, v0
	v_sub_f32_e32 v68, v69, v79
	v_mul_f32_e32 v0, v77, v0
	v_sub_f32_e32 v68, v78, v68
	v_add_f32_e32 v0, v68, v0
	v_add_f32_e32 v70, v69, v0
	v_mul_f32_e32 v72, v70, v70
	v_fmamk_f32 v68, v72, 0x3e9b6dac, v231
	v_fmaak_f32 v191, v72, v68, 0x3f2aaada
	v_cvt_f32_i32_e32 v68, v30
	v_sub_f32_e32 v30, v70, v69
	v_mul_f32_e32 v69, v70, v72
	v_ldexp_f32 v71, v70, 1
	v_pk_mul_f32 v[72:73], v[68:69], v[190:191]
	v_sub_f32_e32 v0, v0, v30
	v_fma_f32 v70, v68, s7, -v72
	v_fmac_f32_e32 v70, 0xb102e308, v68
	v_pk_add_f32 v[68:69], v[72:73], v[70:71]
	v_ldexp_f32 v0, v0, 1
	v_sub_f32_e32 v30, v69, v71
	v_sub_f32_e32 v30, v73, v30
	v_add_f32_e32 v75, v0, v30
	v_mov_b32_e32 v74, v72
	v_pk_add_f32 v[72:73], v[68:69], v[72:73] neg_lo:[0,1] neg_hi:[0,1]
	v_pk_add_f32 v[76:77], v[68:69], v[74:75]
	v_mov_b32_e32 v71, v68
	v_mov_b32_e32 v73, v77
	v_pk_add_f32 v[78:79], v[70:71], v[72:73] neg_lo:[0,1] neg_hi:[0,1]
	v_pk_add_f32 v[70:71], v[70:71], v[72:73]
	v_mov_b32_e32 v74, v75
	v_pk_add_f32 v[72:73], v[70:71], v[68:69] op_sel:[1,0] op_sel_hi:[0,1] neg_lo:[0,1] neg_hi:[0,1]
	v_pk_add_f32 v[80:81], v[76:77], v[72:73] op_sel_hi:[1,0] neg_lo:[0,1] neg_hi:[0,1]
	v_mov_b32_e32 v76, v77
	v_mov_b32_e32 v77, v71
	v_pk_mov_b32 v[72:73], v[68:69], v[72:73] op_sel:[1,0]
	v_mov_b32_e32 v75, v68
	v_pk_add_f32 v[72:73], v[76:77], v[72:73] neg_lo:[0,1] neg_hi:[0,1]
	v_mov_b32_e32 v80, v78
	v_pk_add_f32 v[68:69], v[74:75], v[72:73] neg_lo:[0,1] neg_hi:[0,1]
	v_mov_b32_e32 v79, v71
	v_pk_add_f32 v[72:73], v[80:81], v[68:69]
	s_waitcnt vmcnt(1)
	v_mul_f32_e32 v30, 0xbfb8aa3b, v88
	v_pk_add_f32 v[74:75], v[72:73], v[72:73] op_sel:[0,1] op_sel_hi:[1,0]
	v_exp_f32_e32 v163, v30
	v_pk_add_f32 v[70:71], v[70:71], v[74:75] op_sel:[1,0] op_sel_hi:[0,1]
	v_mov_b32_e32 v73, v70
	v_pk_add_f32 v[76:77], v[72:73], v[78:79] neg_lo:[0,1] neg_hi:[0,1]
	v_mov_b32_e32 v69, v74
	v_sub_f32_e32 v0, v72, v76
	v_pk_add_f32 v[68:69], v[68:69], v[76:77] neg_lo:[0,1] neg_hi:[0,1]
	v_sub_f32_e32 v0, v78, v0
	v_add_f32_e32 v0, v68, v0
	v_add_f32_e32 v0, v0, v69
	v_add_f32_e32 v0, v70, v0
	v_cndmask_b32_e32 v0, v232, v0, vcc
	v_cmp_ngt_f32_e32 vcc, -1.0, v84
	v_readlane_b32 s14, v254, 43
	v_readlane_b32 s5, v252, 17
	v_cndmask_b32_e32 v0, v233, v0, vcc
	v_cmp_neq_f32_e32 vcc, -1.0, v84
	v_readlane_b32 s8, v252, 20
	v_readlane_b32 s9, v252, 21
	v_cndmask_b32_e32 v0, v234, v0, vcc
	v_cmp_lt_f32_e64 vcc, |v84|, s11
	v_readlane_b32 s12, v252, 24
	v_readlane_b32 s13, v252, 25
	v_cndmask_b32_e32 v124, v0, v84, vcc
	v_add_f32_e32 v0, 1.0, v163
	v_cvt_f64_f32_e32 v[68:69], v0
	v_frexp_exp_i32_f64_e32 v68, v[68:69]
	global_load_ushort v69, v[28:29], off offset:2560
	s_nop 0
	global_load_ushort v4, v[4:5], off
	s_nop 0
	global_load_dword v28, v[24:25], off
	global_load_dword v29, v[24:25], off offset:2048
	s_nop 0
	global_load_dword v24, v[26:27], off
	global_load_dword v25, v[26:27], off offset:2048
	v_frexp_mant_f32_e32 v30, v0
	global_load_ushort v22, v[22:23], off offset:1536
	s_nop 0
	global_load_ushort v20, v[20:21], off offset:512
	s_nop 0
	global_load_ushort v21, v[18:19], off
	s_nop 0
	global_load_ushort v18, v[18:19], off offset:3584
	s_nop 0
	global_load_ushort v19, v[12:13], off offset:3072
	global_load_ushort v23, v[14:15], off offset:2560
	s_nop 0
; template <int MODE>
; __device__ __forceinline__ void lru_unit(const Args& a, int l, int b, int ch, LAS unsigned char* lds) {
;     ...
;     for (int i = 0; i < 35; ++i) { const int t = t0 - 2 + i, tc = t < 0 ? 0 : (t >= SEQ ? SEQ - 1 : t); xraw[i] = xp[(size_t)tc * DIN]; }
;     if (MODE == 1) {
; #pragma unroll
;         for (int t = 0; t < 32; ++t) graw[t] = xp[(size_t)(t0 + t) * DIN + LW];
;     }
;     asm volatile("" ::: "memory");
; #pragma unroll
;     for (int i = 0; i < 35; ++i) { const int t = t0 - 2 + i; xin[i] = (t >= 0 && t < SEQ) ? bf2f(xraw[i]) : 0.f; }
;     if (MODE == 1) {
; #pragma unroll
;         for (int t = 0; t < 32; ++t) gl[t] = gelu_tanh(bf2f(graw[t]));
;     }
;     float xcr[32], hf[32];
; #pragma unroll
;     for (int t = 0; t < 32; ++t) { const float xc = cw0 * xin[t] + cw1 * xin[t + 1] + cw2 * xin[t + 2] + cw3 * xin[t + 3] + cb; xcr[t] = xc; hf[t] = 0.f;
	global_load_ushort v16, v[16:17], off offset:2048
	s_nop 0
	global_load_ushort v17, v[10:11], off offset:1024
	v_add_f32_e32 v5, -1.0, v0
	v_cmp_gt_f32_e32 vcc, s6, v30
	v_sub_f32_e32 v26, v5, v0
	v_add_f32_e32 v26, 1.0, v26
	v_subbrev_co_u32_e32 v68, vcc, 0, v68, vcc
	v_sub_f32_e32 v5, v163, v5
	v_add_f32_e32 v5, v5, v26
	v_sub_u32_e32 v26, 0, v68
	v_ldexp_f32 v0, v0, v26
	v_ldexp_f32 v5, v5, v26
	v_add_f32_e32 v26, -1.0, v0
	v_add_f32_e32 v30, 1.0, v0
	v_add_f32_e32 v27, 1.0, v26
	v_add_f32_e32 v70, -1.0, v30
	v_sub_f32_e32 v27, v0, v27
	v_sub_f32_e32 v0, v0, v70
	v_add_f32_e32 v0, v5, v0
	v_add_f32_e32 v70, v30, v0
	v_add_f32_e32 v27, v5, v27
	v_sub_f32_e32 v5, v70, v30
	v_sub_f32_e32 v71, v0, v5
	v_lshlrev_b32_e32 v0, 4, v165
	v_lshl_add_u64 v[10:11], s[28:29], 0, v[0:1]
	v_lshlrev_b32_e32 v0, 7, v164
	v_lshl_add_u64 v[90:91], v[10:11], 0, v[0:1]
	v_add_u32_e32 v10, s14, v82
	v_ashrrev_i32_e32 v11, 31, v10
	v_lshl_add_u64 v[10:11], v[10:11], 2, s[4:5]
	global_load_dword v73, v[10:11], off
	v_lshl_add_u64 v[10:11], s[8:9], 0, v[32:33]
	v_lshl_add_u64 v[12:13], s[12:13], 0, v[32:33]
	global_load_dword v128, v[10:11], off
	global_load_dword v125, v[10:11], off offset:128
	global_load_dword v161, v[10:11], off offset:2048
	global_load_dword v159, v[10:11], off offset:2176
	global_load_dword v129, v[12:13], off
	global_load_dword v127, v[12:13], off offset:128
	global_load_dword v162, v[12:13], off offset:2048
	global_load_dword v160, v[12:13], off offset:2176
	global_load_ushort v0, v[6:7], off offset:1536
	global_load_ushort v30, v[8:9], off offset:1024
	global_load_ushort v33, v[34:35], off offset:512
	s_nop 0
	global_load_ushort v34, v[36:37], off
	global_load_ushort v35, v[36:37], off offset:3584
	s_nop 0
	global_load_ushort v36, v[38:39], off offset:3072
	global_load_ushort v37, v[40:41], off offset:2560
	s_nop 0
	global_load_ushort v38, v[42:43], off offset:2048
	global_load_ushort v39, v[44:45], off offset:1536
	global_load_ushort v40, v[46:47], off offset:1024
	global_load_ushort v41, v[48:49], off offset:512
	s_nop 0
	global_load_ushort v42, v[50:51], off
	global_load_ushort v43, v[50:51], off offset:3584
	global_load_ushort v44, v[52:53], off offset:3072
	global_load_ushort v45, v[54:55], off offset:2560
	global_load_ushort v46, v[56:57], off offset:2048
	global_load_ushort v47, v[58:59], off offset:1536
	global_load_ushort v48, v[60:61], off offset:512
	global_load_ushort v49, v[62:63], off offset:1024
	v_lshlrev_b32_e32 v9, 16, v87
	v_lshlrev_b32_e32 v12, 16, v85
	v_and_b32_e32 v84, 63, v66
	v_lshl_add_u32 v32, v84, 1, s0
	v_rcp_f32_e32 v72, v70
	v_add_f32_e32 v5, v26, v27
	v_add_co_u32_e32 v108, vcc, s60, v90
	v_lshl_add_u64 v[122:123], s[44:45], 0, v[2:3]
	s_nop 0
	v_addc_co_u32_e32 v109, vcc, 0, v91, vcc
	s_mov_b32 s1, 0x11f00000
	v_lshlrev_b64 v[82:83], 3, v[82:83]
	v_readlane_b32 s16, v252, 28
	v_readlane_b32 s17, v252, 29
	v_readlane_b32 s18, v252, 30
	v_readlane_b32 s19, v252, 31
	v_readlane_b32 s15, v254, 44
	s_mov_b64 s[8:9], s[26:27]
	s_waitcnt vmcnt(41)
	v_lshlrev_b32_e32 v13, 16, v69
	s_waitcnt vmcnt(40)
	v_lshlrev_b32_e32 v8, 16, v4
	s_waitcnt vmcnt(38)
	v_pk_mul_f32 v[6:7], v[28:29], v[64:65]
	s_nop 0
	v_add_f32_e32 v4, v6, v7
	s_waitcnt vmcnt(36)
	v_pk_mul_f32 v[10:11], v[24:25], v[8:9]
	v_pk_mov_b32 v[6:7], v[64:65], v[8:9] op_sel:[1,0]
	v_add_f32_e32 v4, v10, v4
	v_add_f32_e32 v4, v11, v4
	v_pk_mul_f32 v[6:7], v[28:29], v[6:7]
	v_pk_mul_f32 v[10:11], v[28:29], v[8:9]
	v_pk_mov_b32 v[8:9], v[8:9], v[12:13] op_sel:[1,0]
	v_add_f32_e32 v6, v6, v7
	v_pk_mul_f32 v[14:15], v[24:25], v[8:9]
	v_add_f32_e32 v10, v10, v11
	v_add_f32_e32 v6, v6, v14
	v_add_f32_e32 v50, v6, v15
	v_pk_mul_f32 v[6:7], v[24:25], v[12:13]
	s_waitcnt vmcnt(35)
	v_lshlrev_b32_e32 v11, 16, v22
	v_add_f32_e32 v6, v10, v6
	v_lshlrev_b32_e32 v10, 16, v67
	v_add_f32_e32 v51, v6, v7
	v_pk_mul_f32 v[6:7], v[28:29], v[8:9]
	v_pk_mul_f32 v[8:9], v[28:29], v[12:13]
	v_pk_mov_b32 v[12:13], v[12:13], v[10:11] op_sel:[1,0]
	v_add_f32_e32 v6, v6, v7
	v_pk_mul_f32 v[14:15], v[24:25], v[12:13]
	v_add_f32_e32 v8, v8, v9
	v_add_f32_e32 v6, v6, v14
	v_add_f32_e32 v22, v6, v15
	v_pk_mul_f32 v[6:7], v[24:25], v[10:11]
	s_waitcnt vmcnt(27)
	v_add_f32_e32 v85, v73, v4
	v_add_f32_e32 v6, v8, v6
	v_add_f32_e32 v52, v6, v7
	v_pk_mul_f32 v[6:7], v[28:29], v[12:13]
	v_lshlrev_b32_e32 v13, 16, v20
	v_lshlrev_b32_e32 v12, 16, v17
	v_pk_mul_f32 v[8:9], v[28:29], v[10:11]
	v_pk_mov_b32 v[10:11], v[10:11], v[12:13] op_sel:[1,0]
	v_add_f32_e32 v6, v6, v7
	v_pk_mul_f32 v[14:15], v[24:25], v[10:11]
	v_add_f32_e32 v8, v8, v9
	v_add_f32_e32 v6, v6, v14
	v_add_f32_e32 v17, v6, v15
	v_pk_mul_f32 v[6:7], v[24:25], v[12:13]
	v_add_f32_e32 v130, v73, v51
	v_add_f32_e32 v6, v8, v6
	v_add_f32_e32 v20, v6, v7
	v_pk_mul_f32 v[6:7], v[28:29], v[10:11]
	v_lshlrev_b32_e32 v11, 16, v18
	v_lshlrev_b32_e32 v10, 16, v21
	v_pk_mul_f32 v[8:9], v[28:29], v[12:13]
	v_pk_mov_b32 v[12:13], v[12:13], v[10:11] op_sel:[1,0]
	v_add_f32_e32 v6, v6, v7
	v_pk_mul_f32 v[14:15], v[24:25], v[12:13]
	v_add_f32_e32 v8, v8, v9
	v_add_f32_e32 v6, v6, v14
	v_add_f32_e32 v18, v6, v15
	v_pk_mul_f32 v[6:7], v[24:25], v[10:11]
	v_add_f32_e32 v131, v73, v22
	v_add_f32_e32 v6, v8, v6
	v_add_f32_e32 v21, v6, v7
	v_pk_mul_f32 v[6:7], v[28:29], v[12:13]
	v_lshlrev_b32_e32 v13, 16, v23
	v_lshlrev_b32_e32 v12, 16, v19
	v_pk_mul_f32 v[8:9], v[28:29], v[10:11]
	v_pk_mov_b32 v[10:11], v[10:11], v[12:13] op_sel:[1,0]
	v_add_f32_e32 v6, v6, v7
	v_pk_mul_f32 v[14:15], v[24:25], v[10:11]
	v_add_f32_e32 v8, v8, v9
	v_add_f32_e32 v6, v6, v14
	v_add_f32_e32 v19, v6, v15
	v_pk_mul_f32 v[6:7], v[24:25], v[12:13]
	v_add_f32_e32 v132, v73, v52
	v_add_f32_e32 v6, v8, v6
	v_add_f32_e32 v23, v6, v7
	v_pk_mul_f32 v[6:7], v[28:29], v[10:11]
	s_waitcnt vmcnt(18)
; #define LAS __attribute__((address_space(3)))
; __device__ __forceinline__ unsigned f2bf(float f) { unsigned u = __builtin_bit_cast(unsigned, f); return (u + 0x7fffu + ((u >> 16) & 1u)) >> 16; }
; template <int MODE>
; __device__ __forceinline__ void lru_unit(const Args& a, int l, int b, int ch, LAS unsigned char* lds) {
;     ...
;     for (int t = 0; t < 32; ++t) { const float xc = cw0 * xin[t] + cw1 * xin[t + 1] + cw2 * xin[t + 2] + cw3 * xin[t + 3] + cb; xcr[t] = xc; hf[t] = 0.f;
;         *(LAS bf16*)(xcb + t * 144 + lane * 2) = (bf16)f2bf(xc); }
	v_lshlrev_b32_e32 v11, 16, v0
	v_lshlrev_b32_e32 v10, 16, v16
	v_pk_mul_f32 v[8:9], v[28:29], v[12:13]
	v_pk_mov_b32 v[12:13], v[12:13], v[10:11] op_sel:[1,0]
	v_add_f32_e32 v0, v6, v7
	v_pk_mul_f32 v[14:15], v[24:25], v[12:13]
	v_pk_mul_f32 v[6:7], v[24:25], v[10:11]
	v_add_f32_e32 v0, v0, v14
	v_add_f32_e32 v16, v0, v15
	v_add_f32_e32 v0, v8, v9
	v_add_f32_e32 v0, v0, v6
	v_add_f32_e32 v53, v0, v7
	v_pk_mul_f32 v[6:7], v[28:29], v[12:13]
	s_waitcnt vmcnt(16)
	v_lshlrev_b32_e32 v13, 16, v33
	v_lshlrev_b32_e32 v12, 16, v30
	v_pk_mul_f32 v[8:9], v[28:29], v[10:11]
	v_pk_mov_b32 v[10:11], v[10:11], v[12:13] op_sel:[1,0]
	v_add_f32_e32 v0, v6, v7
	v_pk_mul_f32 v[14:15], v[24:25], v[10:11]
	v_pk_mul_f32 v[6:7], v[24:25], v[12:13]
	v_add_f32_e32 v0, v0, v14
	v_add_f32_e32 v33, v0, v15
	v_add_f32_e32 v0, v8, v9
	v_add_f32_e32 v0, v0, v6
	v_add_f32_e32 v54, v0, v7
	v_pk_mul_f32 v[6:7], v[28:29], v[10:11]
	s_waitcnt vmcnt(14)
	v_lshlrev_b32_e32 v11, 16, v35
	v_lshlrev_b32_e32 v10, 16, v34
	v_pk_mul_f32 v[8:9], v[28:29], v[12:13]
	v_pk_mov_b32 v[12:13], v[12:13], v[10:11] op_sel:[1,0]
	v_add_f32_e32 v0, v6, v7
	v_pk_mul_f32 v[14:15], v[24:25], v[12:13]
	v_pk_mul_f32 v[6:7], v[24:25], v[10:11]
	v_add_f32_e32 v0, v0, v14
	v_add_f32_e32 v34, v0, v15
	v_add_f32_e32 v0, v8, v9
	v_add_f32_e32 v0, v0, v6
	v_add_f32_e32 v35, v0, v7
	v_pk_mul_f32 v[6:7], v[28:29], v[12:13]
	s_waitcnt vmcnt(12)
	v_lshlrev_b32_e32 v13, 16, v37
	v_lshlrev_b32_e32 v12, 16, v36
	v_pk_mul_f32 v[8:9], v[28:29], v[10:11]
	v_pk_mov_b32 v[10:11], v[10:11], v[12:13] op_sel:[1,0]
	v_add_f32_e32 v0, v6, v7
	v_pk_mul_f32 v[14:15], v[24:25], v[10:11]
	v_pk_mul_f32 v[6:7], v[24:25], v[12:13]
	v_add_f32_e32 v0, v0, v14
	v_add_f32_e32 v36, v0, v15
	v_add_f32_e32 v0, v8, v9
	v_add_f32_e32 v0, v0, v6
	v_add_f32_e32 v37, v0, v7
	v_pk_mul_f32 v[6:7], v[28:29], v[10:11]
	s_waitcnt vmcnt(10)
	v_lshlrev_b32_e32 v11, 16, v39
	v_lshlrev_b32_e32 v10, 16, v38
	v_pk_mul_f32 v[8:9], v[28:29], v[12:13]
	v_pk_mov_b32 v[12:13], v[12:13], v[10:11] op_sel:[1,0]
	v_add_f32_e32 v0, v6, v7
	v_pk_mul_f32 v[14:15], v[24:25], v[12:13]
	v_pk_mul_f32 v[6:7], v[24:25], v[10:11]
	v_add_f32_e32 v0, v0, v14
	v_add_f32_e32 v38, v0, v15
	v_add_f32_e32 v0, v8, v9
	v_add_f32_e32 v0, v0, v6
	v_add_f32_e32 v39, v0, v7
	v_pk_mul_f32 v[6:7], v[28:29], v[12:13]
	s_waitcnt vmcnt(8)
	v_lshlrev_b32_e32 v13, 16, v41
	v_lshlrev_b32_e32 v12, 16, v40
	v_pk_mul_f32 v[8:9], v[28:29], v[10:11]
	v_pk_mov_b32 v[10:11], v[10:11], v[12:13] op_sel:[1,0]
	v_add_f32_e32 v0, v6, v7
	v_pk_mul_f32 v[14:15], v[24:25], v[10:11]
	v_pk_mul_f32 v[6:7], v[24:25], v[12:13]
	v_add_f32_e32 v0, v0, v14
	v_add_f32_e32 v40, v0, v15
	v_add_f32_e32 v0, v8, v9
	v_add_f32_e32 v0, v0, v6
	v_add_f32_e32 v41, v0, v7
	v_pk_mul_f32 v[6:7], v[28:29], v[10:11]
	s_waitcnt vmcnt(6)
	v_lshlrev_b32_e32 v11, 16, v43
	v_lshlrev_b32_e32 v10, 16, v42
	v_pk_mul_f32 v[8:9], v[28:29], v[12:13]
	v_pk_mov_b32 v[12:13], v[12:13], v[10:11] op_sel:[1,0]
	v_add_f32_e32 v0, v6, v7
	v_pk_mul_f32 v[14:15], v[24:25], v[12:13]
	v_pk_mul_f32 v[6:7], v[24:25], v[10:11]
	v_add_f32_e32 v0, v0, v14
	v_add_f32_e32 v42, v0, v15
	v_add_f32_e32 v0, v8, v9
	v_add_f32_e32 v0, v0, v6
	v_add_f32_e32 v43, v0, v7
	v_pk_mul_f32 v[6:7], v[28:29], v[12:13]
	s_waitcnt vmcnt(4)
	v_lshlrev_b32_e32 v13, 16, v45
	v_lshlrev_b32_e32 v12, 16, v44
	v_pk_mul_f32 v[8:9], v[28:29], v[10:11]
	v_pk_mov_b32 v[10:11], v[10:11], v[12:13] op_sel:[1,0]
	v_add_f32_e32 v0, v6, v7
	v_pk_mul_f32 v[14:15], v[24:25], v[10:11]
	v_pk_mul_f32 v[6:7], v[24:25], v[12:13]
	v_add_f32_e32 v0, v0, v14
	v_add_f32_e32 v44, v0, v15
	v_add_f32_e32 v0, v8, v9
	v_add_f32_e32 v0, v0, v6
	v_add_f32_e32 v45, v0, v7
	v_pk_mul_f32 v[6:7], v[28:29], v[10:11]
	s_waitcnt vmcnt(2)
	v_lshlrev_b32_e32 v11, 16, v47
	v_lshlrev_b32_e32 v10, 16, v46
	v_pk_mul_f32 v[8:9], v[28:29], v[12:13]
	v_pk_mov_b32 v[12:13], v[12:13], v[10:11] op_sel:[1,0]
	v_add_f32_e32 v0, v6, v7
	v_pk_mul_f32 v[14:15], v[24:25], v[12:13]
	v_pk_mul_f32 v[6:7], v[24:25], v[10:11]
	v_add_f32_e32 v0, v0, v14
	v_add_f32_e32 v46, v0, v15
	v_add_f32_e32 v0, v8, v9
	v_add_f32_e32 v0, v0, v6
	v_add_f32_e32 v47, v0, v7
	v_pk_mul_f32 v[6:7], v[28:29], v[12:13]
	s_waitcnt vmcnt(0)
	v_lshlrev_b32_e32 v12, 16, v49
	v_lshlrev_b32_e32 v13, 16, v48
	v_pk_mul_f32 v[8:9], v[28:29], v[10:11]
	v_pk_mov_b32 v[10:11], v[10:11], v[12:13] op_sel:[1,0]
	v_add_f32_e32 v0, v6, v7
	v_pk_mul_f32 v[14:15], v[24:25], v[10:11]
	v_pk_mul_f32 v[6:7], v[24:25], v[12:13]
	v_add_f32_e32 v0, v0, v14
	v_add_f32_e32 v14, v0, v15
	v_add_f32_e32 v0, v8, v9
	v_add_f32_e32 v0, v0, v6
	v_add_f32_e32 v12, v0, v7
	v_pk_mul_f32 v[6:7], v[28:29], v[10:11]
	v_mov_b32_e32 v30, v13
	v_pk_mul_f32 v[8:9], v[24:25], v[30:31]
	v_add_f32_e32 v0, v6, v7
	v_add_f32_e32 v0, v0, v8
	v_add_f32_e32 v0, v0, v9
	v_add_f32_e32 v87, v73, v0
	v_bfe_u32 v0, v87, 16, 1
	v_add3_u32 v0, v87, v0, s91
	ds_write_b16_d16_hi v32, v0 offset:4464
	v_bfe_u32 v0, v85, 16, 1
	v_add3_u32 v0, v85, v0, s91
	ds_write_b16_d16_hi v32, v0
	v_add_f32_e32 v0, v73, v50
	v_bfe_u32 v4, v0, 16, 1
	v_add3_u32 v4, v0, v4, s91
	ds_write_b16_d16_hi v32, v4 offset:144
	v_bfe_u32 v4, v130, 16, 1
	v_add3_u32 v4, v130, v4, s91
	ds_write_b16_d16_hi v32, v4 offset:288
	v_bfe_u32 v4, v131, 16, 1
	v_add3_u32 v4, v131, v4, s91
	ds_write_b16_d16_hi v32, v4 offset:432
	v_bfe_u32 v4, v132, 16, 1
	v_add3_u32 v4, v132, v4, s91
	v_add_f32_e32 v133, v73, v17
	ds_write_b16_d16_hi v32, v4 offset:576
	v_bfe_u32 v4, v133, 16, 1
	v_add3_u32 v4, v133, v4, s91
	v_add_f32_e32 v134, v73, v20
	ds_write_b16_d16_hi v32, v4 offset:720
	v_bfe_u32 v4, v134, 16, 1
	v_add3_u32 v4, v134, v4, s91
	v_add_f32_e32 v135, v73, v18
; #define LAS __attribute__((address_space(3)))
; __device__ __forceinline__ unsigned f2bf(float f) { unsigned u = __builtin_bit_cast(unsigned, f); return (u + 0x7fffu + ((u >> 16) & 1u)) >> 16; }
; #define LDS_WAVE_SYNC() asm volatile("s_waitcnt lgkmcnt(0)" ::: "memory")
; template <int DIR, int MODE> ...
;     ...
;         const bf16* wr_ = wl + (size_t)((DIR * 8 + w) * 2) * 4096 + (nt * 32 + r32) * 64 + 8 * h;
; #pragma unroll
;         for (int ks = 0; ks < 4; ++ks) {
;             const bf16x8 bR = *(const bf16x8*)(wr_ + 16 * ks), bI = *(const bf16x8*)(wr_ + 4096 + 16 * ks);
; template <int MODE>
; __device__ __forceinline__ void lru_unit(const Args& a, int l, int b, int ch, LAS unsigned char* lds) {
;     ...
;     for (int t = 0; t < 32; ++t) { const float xc = cw0 * xin[t] + cw1 * xin[t + 1] + cw2 * xin[t + 2] + cw3 * xin[t + 3] + cb; xcr[t] = xc; hf[t] = 0.f;
;         *(LAS bf16*)(xcb + t * 144 + lane * 2) = (bf16)f2bf(xc); }
; #pragma unroll
;     for (int d = 0; d < 2; ++d)
; #pragma unroll
;         for (int nt = 0; nt < 2; ++nt) { prm[d][nt][0] *= -1.4426950408889634f; prm[d][nt][1] *= -1.4426950408889634f;
;             prm[d][nt][2] = -8.f * 1.4426950408889634f * log1pf(__expf(-prm[d][nt][2])); }
;     LDS_WAVE_SYNC();
;     bf16x8 af[4];
; #pragma unroll
;     for (int ks = 0; ks < 4; ++ks) af[ks] = *(const LAS bf16x8*)(xcb + r32 * 144 + (16 * ks + 8 * h) * 2);
;     const bf16* wl = (const bf16*)(a.ws + WS_W) + (size_t)l * W_LAYER + W_LRU;
	ds_write_b16_d16_hi v32, v4 offset:864
	v_bfe_u32 v4, v135, 16, 1
	v_add3_u32 v4, v135, v4, s91
	v_add_f32_e32 v136, v73, v21
	ds_write_b16_d16_hi v32, v4 offset:1008
	v_bfe_u32 v4, v136, 16, 1
	v_add3_u32 v4, v136, v4, s91
	v_add_f32_e32 v137, v73, v19
	ds_write_b16_d16_hi v32, v4 offset:1152
	v_bfe_u32 v4, v137, 16, 1
	v_add3_u32 v4, v137, v4, s91
	v_add_f32_e32 v138, v73, v23
	ds_write_b16_d16_hi v32, v4 offset:1296
	v_bfe_u32 v4, v138, 16, 1
	v_add3_u32 v4, v138, v4, s91
	v_add_f32_e32 v139, v73, v16
	ds_write_b16_d16_hi v32, v4 offset:1440
	v_bfe_u32 v4, v139, 16, 1
	v_add3_u32 v4, v139, v4, s91
	v_add_f32_e32 v140, v73, v53
	ds_write_b16_d16_hi v32, v4 offset:1584
	v_bfe_u32 v4, v140, 16, 1
	v_add3_u32 v4, v140, v4, s91
	v_add_f32_e32 v141, v73, v33
	ds_write_b16_d16_hi v32, v4 offset:1728
	v_bfe_u32 v4, v141, 16, 1
	v_add3_u32 v4, v141, v4, s91
	v_add_f32_e32 v142, v73, v54
	ds_write_b16_d16_hi v32, v4 offset:1872
	v_bfe_u32 v4, v142, 16, 1
	v_add3_u32 v4, v142, v4, s91
	v_add_f32_e32 v143, v73, v34
	ds_write_b16_d16_hi v32, v4 offset:2016
	v_bfe_u32 v4, v143, 16, 1
	v_add3_u32 v4, v143, v4, s91
	v_add_f32_e32 v144, v73, v35
	ds_write_b16_d16_hi v32, v4 offset:2160
	v_bfe_u32 v4, v144, 16, 1
	v_add3_u32 v4, v144, v4, s91
	v_add_f32_e32 v145, v73, v36
	ds_write_b16_d16_hi v32, v4 offset:2304
	v_bfe_u32 v4, v145, 16, 1
	v_add3_u32 v4, v145, v4, s91
	v_add_f32_e32 v146, v73, v37
	ds_write_b16_d16_hi v32, v4 offset:2448
	v_bfe_u32 v4, v146, 16, 1
	v_add3_u32 v4, v146, v4, s91
	v_add_f32_e32 v147, v73, v38
	ds_write_b16_d16_hi v32, v4 offset:2592
	v_bfe_u32 v4, v147, 16, 1
	v_add3_u32 v4, v147, v4, s91
	v_add_f32_e32 v148, v73, v39
	ds_write_b16_d16_hi v32, v4 offset:2736
	v_bfe_u32 v4, v148, 16, 1
	v_add3_u32 v4, v148, v4, s91
	v_add_f32_e32 v149, v73, v40
	ds_write_b16_d16_hi v32, v4 offset:2880
	v_bfe_u32 v4, v149, 16, 1
	v_add3_u32 v4, v149, v4, s91
	v_add_f32_e32 v150, v73, v41
	ds_write_b16_d16_hi v32, v4 offset:3024
	v_bfe_u32 v4, v150, 16, 1
	v_add3_u32 v4, v150, v4, s91
	v_add_f32_e32 v151, v73, v42
	ds_write_b16_d16_hi v32, v4 offset:3168
	v_bfe_u32 v4, v151, 16, 1
	v_add3_u32 v4, v151, v4, s91
	v_add_f32_e32 v152, v73, v43
	ds_write_b16_d16_hi v32, v4 offset:3312
	v_bfe_u32 v4, v152, 16, 1
	v_add3_u32 v4, v152, v4, s91
	v_add_f32_e32 v153, v73, v44
	ds_write_b16_d16_hi v32, v4 offset:3456
	v_bfe_u32 v4, v153, 16, 1
	v_add3_u32 v4, v153, v4, s91
	v_add_f32_e32 v154, v73, v45
	ds_write_b16_d16_hi v32, v4 offset:3600
	v_bfe_u32 v4, v154, 16, 1
	v_add3_u32 v4, v154, v4, s91
	v_add_f32_e32 v155, v73, v46
	ds_write_b16_d16_hi v32, v4 offset:3744
	v_bfe_u32 v4, v155, 16, 1
	v_add3_u32 v4, v155, v4, s91
	v_add_f32_e32 v156, v73, v47
	ds_write_b16_d16_hi v32, v4 offset:3888
	v_bfe_u32 v4, v156, 16, 1
	v_add3_u32 v4, v156, v4, s91
	v_add_f32_e32 v157, v73, v14
	ds_write_b16_d16_hi v32, v4 offset:4032
	v_bfe_u32 v4, v157, 16, 1
	v_add3_u32 v4, v157, v4, s91
	v_add_f32_e32 v158, v73, v12
	ds_write_b16_d16_hi v32, v4 offset:4176
	v_bfe_u32 v4, v158, 16, 1
	v_add3_u32 v4, v158, v4, s91
	ds_write_b16_d16_hi v32, v4 offset:4320
	v_mul_f32_e32 v32, v5, v72
	v_mul_f32_e32 v22, v70, v32
	v_fma_f32 v14, v32, v70, -v22
	v_sub_f32_e32 v4, v5, v26
	v_fmac_f32_e32 v14, v32, v71
	s_waitcnt lgkmcnt(0)
	v_sub_f32_e32 v18, v27, v4
	v_add_f32_e32 v4, v22, v14
	global_load_dwordx4 v[6:9], v[90:91], off
	global_load_dwordx4 v[10:13], v[108:109], off offset:-4096
	v_sub_f32_e32 v23, v5, v4
	v_pk_add_f32 v[16:17], v[4:5], v[22:23] neg_lo:[0,1] neg_hi:[0,1]
	v_mov_b32_e32 v15, v4
	v_pk_add_f32 v[4:5], v[16:17], v[14:15] neg_lo:[0,1] neg_hi:[0,1]
	v_add_co_u32_e32 v34, vcc, s59, v90
	v_add_f32_e32 v5, v18, v5
	v_add_f32_e32 v4, v4, v5
	v_add_f32_e32 v5, v23, v4
	v_mul_f32_e32 v33, v72, v5
	v_addc_co_u32_e32 v35, vcc, 0, v91, vcc
	v_mul_f32_e32 v26, v70, v33
	global_load_dwordx4 v[14:17], v[90:91], off offset:32
	global_load_dwordx4 v[18:21], v[34:35], off offset:32
	v_fma_f32 v28, v33, v70, -v26
	v_fmac_f32_e32 v28, v33, v71
	v_sub_f32_e32 v22, v23, v5
	v_add_f32_e32 v36, v4, v22
	v_add_f32_e32 v4, v26, v28
	v_sub_f32_e32 v27, v5, v4
	v_pk_add_f32 v[30:31], v[4:5], v[26:27] neg_lo:[0,1] neg_hi:[0,1]
	v_mov_b32_e32 v29, v4
	v_pk_add_f32 v[4:5], v[30:31], v[28:29] neg_lo:[0,1] neg_hi:[0,1]
	global_load_dwordx4 v[22:25], v[90:91], off offset:64
	v_add_f32_e32 v5, v36, v5
	v_add_f32_e32 v4, v4, v5
	v_add_f32_e32 v4, v27, v4
	global_load_dwordx4 v[26:29], v[34:35], off offset:64
	v_add_f32_e32 v5, v32, v33
	v_sub_f32_e32 v30, v5, v32
	v_mul_f32_e32 v4, v72, v4
	v_sub_f32_e32 v30, v33, v30
	v_add_f32_e32 v36, v30, v4
	global_load_dwordx4 v[30:33], v[90:91], off offset:96
	global_load_dwordx4 v[104:107], v[34:35], off offset:96
	v_add_co_u32_e32 v74, vcc, s61, v90
	v_add_f32_e32 v37, v5, v36
	s_nop 0
	v_addc_co_u32_e32 v75, vcc, 0, v91, vcc
	global_load_dwordx4 v[166:169], v[74:75], off
	v_mul_f32_e32 v38, v37, v37
	v_fmamk_f32 v4, v38, 0x3e9b6dac, v231
	v_fmaak_f32 v191, v38, v4, 0x3f2aaada
	v_cvt_f32_i32_e32 v4, v68
	v_sub_f32_e32 v5, v37, v5
	v_sub_f32_e32 v5, v36, v5
	v_ldexp_f32 v39, v5, 1
	v_mul_f32_e32 v5, v37, v38
	v_ldexp_f32 v51, v37, 1
	v_pk_mul_f32 v[36:37], v[4:5], v[190:191]
	global_load_dwordx4 v[174:177], v[74:75], off offset:32
	global_load_dwordx4 v[182:185], v[74:75], off offset:64
	v_fma_f32 v50, v4, s7, -v36
	v_lshrrev_b32_e32 v5, 1, v66
	v_fmac_f32_e32 v50, 0xb102e308, v4
	v_mul_u32_u24_e32 v4, 0x90, v164
	v_and_b32_e32 v5, 16, v5
	v_add3_u32 v110, s0, v4, v5
	ds_read_b128 v[70:73], v110
	ds_read_b128 v[66:69], v110 offset:32
	v_pk_add_f32 v[76:77], v[36:37], v[50:51]
	v_mov_b32_e32 v78, v36
	v_sub_f32_e32 v4, v77, v51
	v_sub_f32_e32 v4, v37, v4
	v_add_f32_e32 v79, v39, v4
	v_pk_add_f32 v[52:53], v[76:77], v[36:37] neg_lo:[0,1] neg_hi:[0,1]
	v_pk_add_f32 v[80:81], v[76:77], v[78:79]
	v_mov_b32_e32 v51, v76
	v_mov_b32_e32 v53, v81
	v_pk_add_f32 v[92:93], v[50:51], v[52:53] neg_lo:[0,1] neg_hi:[0,1]
	global_load_dwordx4 v[170:173], v[74:75], off offset:96
	s_waitcnt vmcnt(11) lgkmcnt(1)
; #define MFMA32(a, b, c) __builtin_amdgcn_mfma_f32_32x32x16_bf16((a), (b), (c), 0, 0, 0)
; template <int DIR, int MODE> ...
;     ...
;     f32x16 accR[2], accI[2];
; #pragma unroll
;     for (int nt = 0; nt < 2; ++nt) {
; #pragma unroll
;         for (int i = 0; i < 16; ++i) { accR[nt][i] = 0.f; accI[nt][i] = 0.f; }
;         const bf16* wr_ = wl + (size_t)((DIR * 8 + w) * 2) * 4096 + (nt * 32 + r32) * 64 + 8 * h;
; #pragma unroll
;         for (int ks = 0; ks < 4; ++ks) {
;             const bf16x8 bR = *(const bf16x8*)(wr_ + 16 * ks), bI = *(const bf16x8*)(wr_ + 4096 + 16 * ks);
;             accR[nt] = MFMA32(af[ks], bR, accR[nt]); accI[nt] = MFMA32(af[ks], bI, accI[nt]); }
;     }
; #pragma unroll
;     for (int nt = 0; nt < 2; ++nt) {
;         const float nba = prm[DIR][nt][0], nbx = prm[DIR][nt][1], k8l = prm[DIR][nt][2];
; #pragma unroll
;         for (int i = 0; i < 16; ++i) {
;             const float d1 = 1.f + __builtin_amdgcn_exp2f(__builtin_fmaf(accR[nt][i], -1.4426950408889634f, nba));
;             const float d2 = 1.f + __builtin_amdgcn_exp2f(__builtin_fmaf(accI[nt][i], -1.4426950408889634f, nbx));
;             const float inv = __builtin_amdgcn_rcpf(d1 * d2), rr = inv * d2, ii = inv * d1;
;             const float av = __builtin_amdgcn_exp2f(k8l * rr);
;             accR[nt][i] = av; accI[nt][i] = __builtin_amdgcn_sqrtf(fmaxf(__builtin_fmaf(-av, av, 1.f), 0.f)) * ii; }
	v_mfma_f32_32x32x16_bf16 v[34:49], v[70:73], v[6:9], 0
	v_add_f32_e64 v8, v50, v52
	v_add_f32_e64 v9, v51, v53
	v_mov_b32_e32 v78, v79
	v_add_f32_e64 v88, v9, -v76
	v_add_f32_e64 v89, v8, -v77
	v_mov_b32_e32 v79, v76
	v_mov_b32_e32 v93, v9
	global_load_dwordx4 v[4:7], v[108:109], off
	global_load_dwordx4 v[178:181], v[108:109], off offset:32
	s_waitcnt vmcnt(12)
	v_mfma_f32_32x32x16_bf16 v[50:65], v[70:73], v[10:13], 0
	v_add_f32_e64 v10, v80, -v88
	v_add_f32_e64 v11, v81, -v88
	v_mov_b32_e32 v12, v81
	v_mov_b32_e32 v13, v9
	v_pk_mov_b32 v[80:81], v[76:77], v[88:89] op_sel:[1,0]
	ds_read_b128 v[74:77], v110 offset:96
	v_pk_add_f32 v[12:13], v[12:13], v[80:81] neg_lo:[0,1] neg_hi:[0,1]
	v_mov_b32_e32 v10, v92
	v_pk_add_f32 v[96:97], v[78:79], v[12:13] neg_lo:[0,1] neg_hi:[0,1]
	ds_read_b128 v[78:81], v110 offset:64
	s_waitcnt vmcnt(11) lgkmcnt(2)
	v_mfma_f32_32x32x16_bf16 v[34:49], v[66:69], v[14:17], v[34:49]
	v_add_f32_e64 v98, v10, v96
	v_add_f32_e64 v99, v11, v97
	v_mul_f32_e32 v97, 0xbfb8aa3b, v128
	v_add_f32_e64 v100, v98, v99
	v_add_f32_e64 v101, v99, v98
	global_load_dwordx4 v[186:189], v[108:109], off offset:64
	global_load_dwordx4 v[200:203], v[108:109], off offset:96
	v_pk_add_f32 v[94:95], v[8:9], v[100:101] op_sel:[1,0] op_sel_hi:[0,1]
	v_mov_b32_e32 v99, v94
	s_waitcnt vmcnt(12)
	v_mfma_f32_32x32x16_bf16 v[50:65], v[66:69], v[18:21], v[50:65]
	v_add_f32_e64 v102, v98, -v92
	v_add_f32_e64 v103, v99, -v93
	v_mul_f32_e32 v99, 0xbfb8aa3b, v129
	v_mul_f32_e32 v93, 0xbfb8aa3b, v127
	v_lshl_add_u64 v[88:89], s[46:47], 0, v[2:3]
	v_mul_f32_e32 v95, 0xbfb8aa3b, v125
	v_add_co_u32_e32 v120, vcc, s1, v88
	s_waitcnt vmcnt(11) lgkmcnt(0)
	v_mfma_f32_32x32x16_bf16 v[34:49], v[78:81], v[22:25], v[34:49]
	v_addc_co_u32_e32 v121, vcc, 0, v89, vcc
	s_mov_b32 s1, 0x11f01000
	v_add_co_u32_e32 v118, vcc, s1, v88
	s_mov_b32 s1, 0x11f02000
	s_nop 0
	v_addc_co_u32_e32 v119, vcc, 0, v89, vcc
	s_waitcnt vmcnt(10)
	v_mfma_f32_32x32x16_bf16 v[50:65], v[78:81], v[26:29], v[50:65]
	v_add_co_u32_e32 v116, vcc, s1, v88
	s_mov_b32 s1, 0x11f03000
	s_nop 0
	v_addc_co_u32_e32 v117, vcc, 0, v89, vcc
	v_add_co_u32_e32 v114, vcc, s1, v88
	s_waitcnt vmcnt(9)
	v_mfma_f32_32x32x16_bf16 v[34:49], v[74:77], v[30:33], v[34:49]
	v_addc_co_u32_e32 v115, vcc, 0, v89, vcc
	s_mov_b32 s1, 0x11f04000
	v_add_co_u32_e32 v112, vcc, s1, v88
	s_mov_b32 s1, 0x11f05000
	s_nop 0
	v_addc_co_u32_e32 v113, vcc, 0, v89, vcc
	s_waitcnt vmcnt(8)
	v_mfma_f32_32x32x16_bf16 v[50:65], v[74:77], v[104:107], v[50:65]
	s_nop 3
	v_fmamk_f32 v34, v34, 0xbfb8aa3b, v97
	v_fmamk_f32 v101, v35, 0xbfb8aa3b, v97
	v_exp_f32_e32 v34, v34
	v_fmamk_f32 v129, v36, 0xbfb8aa3b, v97
	v_fmamk_f32 v38, v38, 0xbfb8aa3b, v97
	v_fmamk_f32 v39, v39, 0xbfb8aa3b, v97
	v_fmamk_f32 v40, v40, 0xbfb8aa3b, v97
	s_nop 0
	v_fmamk_f32 v50, v50, 0xbfb8aa3b, v99
	v_exp_f32_e32 v35, v50
	v_fmamk_f32 v51, v51, 0xbfb8aa3b, v99
	s_waitcnt vmcnt(7)
	v_mfma_f32_32x32x16_bf16 v[18:33], v[70:73], v[166:169], 0
	v_fmamk_f32 v166, v37, 0xbfb8aa3b, v97
	v_add_f32_e64 v34, v34, 1.0
	v_add_f32_e64 v35, v35, 1.0
	v_exp_f32_e32 v37, v51
	v_mul_f32_e32 v36, v34, v35
	v_rcp_f32_e32 v193, v36
	v_exp_f32_e32 v36, v101
	v_mov_b32_e32 v127, v35
	v_fmamk_f32 v41, v41, 0xbfb8aa3b, v97
	v_fmamk_f32 v42, v42, 0xbfb8aa3b, v97
	v_fmamk_f32 v43, v43, 0xbfb8aa3b, v97
	v_fmamk_f32 v44, v44, 0xbfb8aa3b, v97
	v_fmamk_f32 v45, v45, 0xbfb8aa3b, v97
	v_fmamk_f32 v46, v46, 0xbfb8aa3b, v97
	v_fmamk_f32 v167, v47, 0xbfb8aa3b, v97
	v_fmamk_f32 v168, v48, 0xbfb8aa3b, v97
	v_fmac_f32_e32 v97, 0xbfb8aa3b, v49
	v_pk_mul_f32 v[48:49], v[126:127], v[192:193]
	v_pk_add_f32 v[36:37], v[36:37], 1.0 op_sel_hi:[1,0]
	v_mul_f32_e32 v35, v48, v49
	v_exp_f32_e32 v128, v35
	v_mul_f32_e32 v35, v36, v37
	v_rcp_f32_e32 v49, v35
	v_mul_f32_e32 v50, v34, v193
	v_fma_f32 v34, -v128, v128, 1.0
	v_fmamk_f32 v47, v52, 0xbfb8aa3b, v99
	v_mul_f32_e32 v35, v37, v49
	v_mul_f32_e32 v35, v48, v35
	v_exp_f32_e32 v126, v35
	v_max_f32_e32 v34, 0, v34
	v_sqrt_f32_e32 v37, v34
	v_exp_f32_e32 v34, v129
	v_exp_f32_e32 v35, v47
	v_fma_f32 v47, -v126, v126, 1.0
	v_max_f32_e32 v47, 0, v47
	v_sqrt_f32_e32 v47, v47
	v_pk_add_f32 v[34:35], v[34:35], 1.0 op_sel_hi:[1,0]
	v_fmamk_f32 v52, v53, 0xbfb8aa3b, v99
	v_mul_f32_e32 v51, v34, v35
	v_rcp_f32_e32 v51, v51
	v_mul_f32_e32 v36, v36, v49
	v_mul_f32_e32 v129, v50, v37
	v_mul_f32_e32 v127, v36, v47
	v_exp_f32_e32 v36, v166
	v_exp_f32_e32 v37, v52
	v_mul_f32_e32 v35, v35, v51
	v_mul_f32_e32 v35, v48, v35
	s_waitcnt vmcnt(6)
; #define MFMA32(a, b, c) __builtin_amdgcn_mfma_f32_32x32x16_bf16((a), (b), (c), 0, 0, 0)
; template <int DIR, int MODE> ...
;     ...
;         for (int ks = 0; ks < 4; ++ks) {
;             const bf16x8 bR = *(const bf16x8*)(wr_ + 16 * ks), bI = *(const bf16x8*)(wr_ + 4096 + 16 * ks);
;             accR[nt] = MFMA32(af[ks], bR, accR[nt]); accI[nt] = MFMA32(af[ks], bI, accI[nt]); }
;     }
; #pragma unroll
;     for (int nt = 0; nt < 2; ++nt) {
;         const float nba = prm[DIR][nt][0], nbx = prm[DIR][nt][1], k8l = prm[DIR][nt][2];
; #pragma unroll
;         for (int i = 0; i < 16; ++i) {
;             const float d1 = 1.f + __builtin_amdgcn_exp2f(__builtin_fmaf(accR[nt][i], -1.4426950408889634f, nba));
;             const float d2 = 1.f + __builtin_amdgcn_exp2f(__builtin_fmaf(accI[nt][i], -1.4426950408889634f, nbx));
;             const float inv = __builtin_amdgcn_rcpf(d1 * d2), rr = inv * d2, ii = inv * d1;
;             const float av = __builtin_amdgcn_exp2f(k8l * rr);
;             accR[nt][i] = av; accI[nt][i] = __builtin_amdgcn_sqrtf(fmaxf(__builtin_fmaf(-av, av, 1.f), 0.f)) * ii; }
	v_mfma_f32_32x32x16_bf16 v[18:33], v[66:69], v[174:177], v[18:33]
	v_add_f32_e64 v36, v36, 1.0
	v_add_f32_e64 v37, v37, 1.0
	v_fmamk_f32 v176, v62, 0xbfb8aa3b, v99
	v_exp_f32_e32 v62, v35
	v_mul_f32_e32 v35, v36, v37
	v_rcp_f32_e32 v47, v35
	v_fmamk_f32 v53, v54, 0xbfb8aa3b, v99
	v_mul_f32_e32 v49, v34, v51
	v_fma_f32 v34, -v62, v62, 1.0
	v_mul_f32_e32 v35, v37, v47
	v_mul_f32_e32 v35, v48, v35
	v_exp_f32_e32 v54, v35
	v_max_f32_e32 v34, 0, v34
	v_sqrt_f32_e32 v37, v34
	v_exp_f32_e32 v34, v38
	v_exp_f32_e32 v35, v53
	v_fma_f32 v38, -v54, v54, 1.0
	v_max_f32_e32 v38, 0, v38
	v_sqrt_f32_e32 v38, v38
	v_pk_add_f32 v[34:35], v[34:35], 1.0 op_sel_hi:[1,0]
	v_fmamk_f32 v169, v55, 0xbfb8aa3b, v99
	v_mul_f32_e32 v50, v34, v35
	v_rcp_f32_e32 v51, v50
	v_mul_f32_e32 v36, v36, v47
	v_fmamk_f32 v177, v63, 0xbfb8aa3b, v99
	v_mul_f32_e32 v63, v49, v37
	v_mul_f32_e32 v55, v36, v38
	v_exp_f32_e32 v36, v39
	v_exp_f32_e32 v37, v169
	v_mul_f32_e32 v35, v35, v51
	v_mul_f32_e32 v35, v48, v35
	v_exp_f32_e32 v50, v35
	v_pk_add_f32 v[36:37], v[36:37], 1.0 op_sel_hi:[1,0]
	v_mul_f32_e32 v39, v34, v51
	v_mul_f32_e32 v35, v36, v37
	v_rcp_f32_e32 v38, v35
	v_fma_f32 v34, -v50, v50, 1.0
	v_fmamk_f32 v56, v56, 0xbfb8aa3b, v99
	v_max_f32_e32 v34, 0, v34
	v_mul_f32_e32 v35, v37, v38
	v_mul_f32_e32 v35, v48, v35
	v_exp_f32_e32 v52, v35
	v_sqrt_f32_e32 v37, v34
	v_exp_f32_e32 v34, v40
	v_exp_f32_e32 v35, v56
	v_fma_f32 v40, -v52, v52, 1.0
	v_max_f32_e32 v40, 0, v40
	v_sqrt_f32_e32 v40, v40
	v_pk_add_f32 v[34:35], v[34:35], 1.0 op_sel_hi:[1,0]
	v_fmamk_f32 v57, v57, 0xbfb8aa3b, v99
	v_mul_f32_e32 v47, v34, v35
	v_rcp_f32_e32 v47, v47
	v_mul_f32_e32 v36, v36, v38
	v_mul_f32_e32 v51, v39, v37
	v_mul_f32_e32 v53, v36, v40
	v_exp_f32_e32 v36, v41
	v_exp_f32_e32 v37, v57
	v_mul_f32_e32 v35, v35, v47
	v_mul_f32_e32 v35, v48, v35
	v_exp_f32_e32 v56, v35
	v_pk_add_f32 v[36:37], v[36:37], 1.0 op_sel_hi:[1,0]
	v_fmamk_f32 v174, v58, 0xbfb8aa3b, v99
	v_mul_f32_e32 v35, v36, v37
	v_rcp_f32_e32 v40, v35
	v_mul_f32_e32 v41, v34, v47
	v_fma_f32 v34, -v56, v56, 1.0
	v_max_f32_e32 v34, 0, v34
	v_mul_f32_e32 v35, v37, v40
	v_mul_f32_e32 v35, v48, v35
	v_exp_f32_e32 v58, v35
	v_sqrt_f32_e32 v37, v34
	v_exp_f32_e32 v34, v42
	v_exp_f32_e32 v35, v174
	v_fma_f32 v38, -v58, v58, 1.0
	v_max_f32_e32 v38, 0, v38
	v_sqrt_f32_e32 v42, v38
	v_pk_add_f32 v[38:39], v[34:35], 1.0 op_sel_hi:[1,0]
	v_fmamk_f32 v175, v59, 0xbfb8aa3b, v99
	v_mul_f32_e32 v34, v38, v39
	v_rcp_f32_e32 v35, v34
	v_mul_f32_e32 v57, v41, v37
	v_mul_f32_e32 v34, v36, v40
	v_exp_f32_e32 v36, v43
	v_exp_f32_e32 v37, v175
	v_mul_f32_e32 v59, v34, v42
	v_mul_f32_e32 v34, v39, v35
	v_mul_f32_e32 v34, v48, v34
	v_pk_add_f32 v[40:41], v[36:37], 1.0 op_sel_hi:[1,0]
	v_exp_f32_e32 v34, v34
	v_mul_f32_e32 v36, v40, v41
	v_rcp_f32_e32 v37, v36
	v_mul_f32_e32 v35, v38, v35
	v_fma_f32 v36, -v34, v34, 1.0
	v_max_f32_e32 v38, 0, v36
	v_mul_f32_e32 v36, v41, v37
	v_mul_f32_e32 v36, v48, v36
	v_exp_f32_e32 v36, v36
	v_fmamk_f32 v60, v60, 0xbfb8aa3b, v99
	v_sqrt_f32_e32 v41, v38
	v_exp_f32_e32 v38, v44
	v_exp_f32_e32 v39, v60
	v_fma_f32 v42, -v36, v36, 1.0
	v_max_f32_e32 v42, 0, v42
	v_sqrt_f32_e32 v44, v42
	v_pk_add_f32 v[42:43], v[38:39], 1.0 op_sel_hi:[1,0]
	v_fmamk_f32 v61, v61, 0xbfb8aa3b, v99
	v_mul_f32_e32 v38, v42, v43
	v_rcp_f32_e32 v39, v38
	v_mul_f32_e32 v35, v35, v41
	v_mul_f32_e32 v37, v40, v37
	v_exp_f32_e32 v40, v45
	v_exp_f32_e32 v41, v61
	v_mul_f32_e32 v38, v43, v39
	v_mul_f32_e32 v37, v37, v44
	v_mul_f32_e32 v38, v48, v38
	v_pk_add_f32 v[44:45], v[40:41], 1.0 op_sel_hi:[1,0]
	v_exp_f32_e32 v38, v38
	v_mul_f32_e32 v40, v44, v45
	v_rcp_f32_e32 v41, v40
	v_mul_f32_e32 v39, v42, v39
	v_fma_f32 v40, -v38, v38, 1.0
	v_max_f32_e32 v42, 0, v40
	v_mul_f32_e32 v40, v45, v41
	v_mul_f32_e32 v40, v48, v40
	v_exp_f32_e32 v40, v40
	v_sqrt_f32_e32 v45, v42
	v_exp_f32_e32 v42, v46
	v_exp_f32_e32 v43, v176
	v_fma_f32 v46, -v40, v40, 1.0
	s_waitcnt vmcnt(3)
	v_mfma_f32_32x32x16_bf16 v[2:17], v[70:73], v[4:7], 0
	v_max_f32_e32 v46, 0, v46
	v_sqrt_f32_e32 v49, v46
	v_pk_add_f32 v[46:47], v[42:43], 1.0 op_sel_hi:[1,0]
	v_mul_f32_e32 v39, v39, v45
	v_mul_f32_e32 v42, v46, v47
	v_rcp_f32_e32 v43, v42
	v_mul_f32_e32 v41, v44, v41
	v_exp_f32_e32 v44, v167
	v_exp_f32_e32 v45, v177
	v_mul_f32_e32 v42, v47, v43
	s_waitcnt vmcnt(2)
	v_mfma_f32_32x32x16_bf16 v[2:17], v[66:69], v[178:181], v[2:17]
	v_mul_f32_e32 v42, v48, v42
	v_add_f32_e64 v60, v44, 1.0
	v_add_f32_e64 v61, v45, 1.0
	v_exp_f32_e32 v42, v42
	v_mul_f32_e32 v44, v60, v61
	v_rcp_f32_e32 v45, v44
	v_mul_f32_e32 v43, v46, v43
	v_fma_f32 v44, -v42, v42, 1.0
	v_max_f32_e32 v46, 0, v44
	v_mul_f32_e32 v44, v61, v45
	v_mul_f32_e32 v44, v48, v44
	v_mfma_f32_32x32x16_bf16 v[18:33], v[78:81], v[182:185], v[18:33]
	v_exp_f32_e32 v44, v44
	v_fmamk_f32 v64, v64, 0xbfb8aa3b, v99
	v_mul_f32_e32 v41, v41, v49
	v_sqrt_f32_e32 v49, v46
	v_exp_f32_e32 v46, v168
	v_exp_f32_e32 v47, v64
	v_fma_f32 v61, -v44, v44, 1.0
	s_waitcnt vmcnt(1)
	v_mfma_f32_32x32x16_bf16 v[2:17], v[78:81], v[186:189], v[2:17]
	v_max_f32_e32 v61, 0, v61
	v_sqrt_f32_e32 v61, v61
	v_pk_add_f32 v[46:47], v[46:47], 1.0 op_sel_hi:[1,0]
	v_fmac_f32_e32 v99, 0xbfb8aa3b, v65
	v_mul_f32_e32 v64, v46, v47
	v_mul_f32_e32 v45, v60, v45
	v_rcp_f32_e32 v64, v64
	v_mfma_f32_32x32x16_bf16 v[18:33], v[74:77], v[170:173], v[18:33]
	v_mul_f32_e32 v45, v45, v61
	v_exp_f32_e32 v60, v97
	v_exp_f32_e32 v61, v99
	v_mul_f32_e32 v47, v47, v64
	v_mul_f32_e32 v43, v43, v49
	v_mul_f32_e32 v49, v46, v64
	v_pk_add_f32 v[60:61], v[60:61], 1.0 op_sel_hi:[1,0]
	s_waitcnt vmcnt(0)
; #define LAS __attribute__((address_space(3)))
; template <int DIR, int MODE> ...
;     ...
;     for (int nt = 0; nt < 2; ++nt) {
;         const float nba = prm[DIR][nt][0], nbx = prm[DIR][nt][1], k8l = prm[DIR][nt][2];
; #pragma unroll
;         for (int i = 0; i < 16; ++i) {
;             const float d1 = 1.f + __builtin_amdgcn_exp2f(__builtin_fmaf(accR[nt][i], -1.4426950408889634f, nba));
;             const float d2 = 1.f + __builtin_amdgcn_exp2f(__builtin_fmaf(accI[nt][i], -1.4426950408889634f, nbx));
;             const float inv = __builtin_amdgcn_rcpf(d1 * d2), rr = inv * d2, ii = inv * d1;
;             const float av = __builtin_amdgcn_exp2f(k8l * rr);
;             accR[nt][i] = av; accI[nt][i] = __builtin_amdgcn_sqrtf(fmaxf(__builtin_fmaf(-av, av, 1.f), 0.f)) * ii; }
;     }
;     float hc = 0.f, ap = 1.f;
;     if (MODE == 1) hc = ((const float*)(a.ws + WS_CAR))[(size_t)((b * NCH + ch) * 2 + DIR) * LW + c];
; #pragma unroll
;     for (int hh = 0; hh < 2; ++hh) {
;         const int half = DIR == 0 ? hh : 1 - hh;
; #pragma unroll
;         for (int nt = 0; nt < 2; ++nt)
; #pragma unroll
;             for (int i = 0; i < 8; ++i) { const int tt = 8 * (i >> 2) + 4 * h + (i & 3);
;                 f32x2 v; v.x = accR[nt][8 * half + i]; v.y = accI[nt][8 * half + i];
;                 *(LAS f32x2*)(au + (tt * 64 + nt * 32 + r32) * 2) = v; }
	v_mfma_f32_32x32x16_bf16 v[2:17], v[74:77], v[200:203], v[2:17]
	v_mul_f32_e32 v46, v48, v47
	v_mul_f32_e32 v47, v60, v61
	v_rcp_f32_e32 v97, v47
	v_fmamk_f32 v18, v18, 0xbfb8aa3b, v95
	v_exp_f32_e32 v46, v46
	v_exp_f32_e32 v64, v18
	v_mul_f32_e32 v61, v61, v97
	s_nop 4
	v_fmamk_f32 v2, v2, 0xbfb8aa3b, v93
	v_exp_f32_e32 v65, v2
	v_fma_f32 v47, -v46, v46, 1.0
	v_mul_f32_e32 v48, v48, v61
	v_max_f32_e32 v47, 0, v47
	v_pk_add_f32 v[64:65], v[64:65], 1.0 op_sel_hi:[1,0]
	v_exp_f32_e32 v48, v48
	v_mul_f32_e32 v18, v64, v65
	v_sqrt_f32_e32 v47, v47
	v_rcp_f32_e32 v193, v18
	v_fma_f32 v2, -v48, v48, 1.0
	v_mov_b32_e32 v125, v65
	v_mul_f32_e32 v47, v49, v47
	v_mul_f32_e32 v49, v60, v97
	v_max_f32_e32 v2, 0, v2
	v_pk_mul_f32 v[60:61], v[124:125], v[192:193]
	v_sqrt_f32_e32 v97, v2
	v_mul_f32_e32 v2, v60, v61
	v_exp_f32_e32 v2, v2
	v_fmamk_f32 v18, v19, 0xbfb8aa3b, v95
	v_fmamk_f32 v3, v3, 0xbfb8aa3b, v93
	v_exp_f32_e32 v18, v18
	v_exp_f32_e32 v19, v3
	v_fma_f32 v3, -v2, v2, 1.0
	v_max_f32_e32 v3, 0, v3
	v_sqrt_f32_e32 v3, v3
	v_pk_add_f32 v[18:19], v[18:19], 1.0 op_sel_hi:[1,0]
	v_mul_f32_e32 v64, v64, v193
	v_mul_f32_e32 v61, v18, v19
	v_rcp_f32_e32 v61, v61
	v_fmamk_f32 v20, v20, 0xbfb8aa3b, v95
	v_fmamk_f32 v4, v4, 0xbfb8aa3b, v93
	v_mul_f32_e32 v3, v64, v3
	v_exp_f32_e32 v64, v20
	v_exp_f32_e32 v65, v4
	v_mul_f32_e32 v19, v19, v61
	v_mul_f32_e32 v4, v60, v19
	v_mul_f32_e32 v20, v18, v61
	v_exp_f32_e32 v166, v4
	v_pk_add_f32 v[18:19], v[64:65], 1.0 op_sel_hi:[1,0]
	v_fmamk_f32 v5, v5, 0xbfb8aa3b, v93
	v_mul_f32_e32 v4, v18, v19
	v_rcp_f32_e32 v61, v4
	v_fma_f32 v4, -v166, v166, 1.0
	v_max_f32_e32 v4, 0, v4
	v_sqrt_f32_e32 v65, v4
	v_mul_f32_e32 v4, v19, v61
	v_mul_f32_e32 v4, v60, v4
	v_exp_f32_e32 v64, v4
	v_fmamk_f32 v4, v21, 0xbfb8aa3b, v95
	v_exp_f32_e32 v4, v4
	v_exp_f32_e32 v5, v5
	v_fma_f32 v19, -v64, v64, 1.0
	v_max_f32_e32 v19, 0, v19
	v_sqrt_f32_e32 v19, v19
	v_pk_add_f32 v[4:5], v[4:5], 1.0 op_sel_hi:[1,0]
	v_mul_f32_e32 v49, v49, v97
	v_mul_f32_e32 v21, v4, v5
	v_rcp_f32_e32 v97, v21
	v_mul_f32_e32 v18, v18, v61
	v_mul_f32_e32 v167, v20, v65
	v_mul_f32_e32 v65, v18, v19
	v_fmamk_f32 v18, v22, 0xbfb8aa3b, v95
	v_fmamk_f32 v6, v6, 0xbfb8aa3b, v93
	v_exp_f32_e32 v20, v18
	v_exp_f32_e32 v21, v6
	v_mul_f32_e32 v5, v5, v97
	v_mul_f32_e32 v19, v4, v97
	v_mul_f32_e32 v4, v60, v5
	v_exp_f32_e32 v18, v4
	v_pk_add_f32 v[4:5], v[20:21], 1.0 op_sel_hi:[1,0]
	v_fmamk_f32 v9, v9, 0xbfb8aa3b, v93
	v_mul_f32_e32 v6, v4, v5
	v_rcp_f32_e32 v61, v6
	v_fma_f32 v6, -v18, v18, 1.0
	v_max_f32_e32 v6, 0, v6
	v_sqrt_f32_e32 v22, v6
	v_mul_f32_e32 v5, v5, v61
	v_mul_f32_e32 v5, v60, v5
	v_fmamk_f32 v6, v23, 0xbfb8aa3b, v95
	v_exp_f32_e32 v20, v6
	v_exp_f32_e32 v6, v5
	v_fmamk_f32 v5, v7, 0xbfb8aa3b, v93
	v_exp_f32_e32 v21, v5
	v_mul_f32_e32 v19, v19, v22
	v_fma_f32 v5, -v6, v6, 1.0
	v_max_f32_e32 v5, 0, v5
	v_pk_add_f32 v[20:21], v[20:21], 1.0 op_sel_hi:[1,0]
	v_sqrt_f32_e32 v5, v5
	v_mul_f32_e32 v7, v20, v21
	v_rcp_f32_e32 v97, v7
	v_fmamk_f32 v7, v24, 0xbfb8aa3b, v95
	v_exp_f32_e32 v22, v7
	v_fmamk_f32 v7, v8, 0xbfb8aa3b, v93
	v_exp_f32_e32 v23, v7
	v_mul_f32_e32 v4, v4, v61
	v_mul_f32_e32 v7, v4, v5
	v_mul_f32_e32 v8, v21, v97
	v_pk_add_f32 v[4:5], v[22:23], 1.0 op_sel_hi:[1,0]
	v_mul_f32_e32 v8, v60, v8
	v_mul_f32_e32 v21, v4, v5
	v_rcp_f32_e32 v21, v21
	v_mul_f32_e32 v24, v20, v97
	v_exp_f32_e32 v8, v8
	v_exp_f32_e32 v23, v9
	v_mul_f32_e32 v5, v5, v21
	v_mul_f32_e32 v5, v60, v5
	v_exp_f32_e32 v20, v5
	v_fma_f32 v5, -v8, v8, 1.0
	v_max_f32_e32 v5, 0, v5
	v_sqrt_f32_e32 v5, v5
	v_fma_f32 v22, -v20, v20, 1.0
	v_max_f32_e32 v22, 0, v22
	v_sqrt_f32_e32 v61, v22
	v_fmamk_f32 v22, v25, 0xbfb8aa3b, v95
	v_exp_f32_e32 v22, v22
	v_mul_f32_e32 v4, v4, v21
	v_mul_f32_e32 v9, v24, v5
	v_mul_f32_e32 v21, v4, v61
	v_pk_add_f32 v[4:5], v[22:23], 1.0 op_sel_hi:[1,0]
	v_lshlrev_b32_e32 v23, 11, v165
	v_lshlrev_b32_e32 v24, 3, v164
	v_mul_f32_e32 v22, v4, v5
	v_add3_u32 v24, s0, v23, v24
	v_rcp_f32_e32 v22, v22
	v_add_u32_e32 v124, 0x1000, v24
	ds_write2_b64 v124, v[128:129], v[2:3] offset0:64 offset1:96
	v_fmamk_f32 v2, v26, 0xbfb8aa3b, v95
	v_fmamk_f32 v3, v10, 0xbfb8aa3b, v93
	v_exp_f32_e32 v2, v2
	v_exp_f32_e32 v3, v3
	v_mul_f32_e32 v5, v5, v22
	v_mul_f32_e32 v5, v60, v5
	v_exp_f32_e32 v10, v5
	v_mul_f32_e32 v25, v4, v22
	v_pk_add_f32 v[4:5], v[2:3], 1.0 op_sel_hi:[1,0]
	v_fmamk_f32 v13, v13, 0xbfb8aa3b, v93
	v_mul_f32_e32 v2, v4, v5
	v_rcp_f32_e32 v3, v2
	v_fma_f32 v2, -v10, v10, 1.0
	v_max_f32_e32 v2, 0, v2
	v_sqrt_f32_e32 v61, v2
	v_mul_f32_e32 v2, v5, v3
	v_fmamk_f32 v5, v27, 0xbfb8aa3b, v95
	v_mul_f32_e32 v2, v60, v2
	v_exp_f32_e32 v22, v5
	v_fmamk_f32 v5, v11, 0xbfb8aa3b, v93
	v_exp_f32_e32 v2, v2
	v_exp_f32_e32 v23, v5
	v_mul_f32_e32 v3, v4, v3
	v_fmamk_f32 v14, v14, 0xbfb8aa3b, v93
	v_fma_f32 v5, -v2, v2, 1.0
	v_pk_add_f32 v[26:27], v[22:23], 1.0 op_sel_hi:[1,0]
	v_max_f32_e32 v5, 0, v5
	v_mul_f32_e32 v11, v26, v27
	v_sqrt_f32_e32 v5, v5
	v_rcp_f32_e32 v97, v11
	v_mul_f32_e32 v11, v25, v61
	ds_write2_b64 v124, v[126:127], v[166:167] offset0:128 offset1:160
	v_mul_f32_e32 v3, v3, v5
	v_mul_f32_e32 v4, v27, v97
	v_fmamk_f32 v5, v28, 0xbfb8aa3b, v95
	v_mul_f32_e32 v4, v60, v4
	v_exp_f32_e32 v22, v5
	v_fmamk_f32 v5, v12, 0xbfb8aa3b, v93
	v_exp_f32_e32 v4, v4
	v_exp_f32_e32 v23, v5
	v_exp_f32_e32 v27, v13
	v_add_u32_e32 v126, 0x1800, v24
	v_fma_f32 v5, -v4, v4, 1.0
	v_pk_add_f32 v[22:23], v[22:23], 1.0 op_sel_hi:[1,0]
	v_max_f32_e32 v5, 0, v5
	v_mul_f32_e32 v12, v22, v23
	v_sqrt_f32_e32 v5, v5
	v_rcp_f32_e32 v25, v12
	v_mul_f32_e32 v12, v26, v97
	ds_write2_b64 v126, v[54:55], v[18:19] offset1:32
	v_mul_f32_e32 v5, v12, v5
	v_mul_f32_e32 v12, v23, v25
	v_fmamk_f32 v23, v29, 0xbfb8aa3b, v95
	v_exp_f32_e32 v26, v23
	v_mul_f32_e32 v12, v60, v12
	v_exp_f32_e32 v12, v12
	v_mul_f32_e32 v22, v22, v25
	v_pk_add_f32 v[26:27], v[26:27], 1.0 op_sel_hi:[1,0]
	v_exp_f32_e32 v29, v14
	v_mul_f32_e32 v23, v26, v27
	v_fma_f32 v13, -v12, v12, 1.0
	v_rcp_f32_e32 v28, v23
	v_max_f32_e32 v13, 0, v13
	v_sqrt_f32_e32 v13, v13
	v_fmamk_f32 v18, v31, 0xbfb8aa3b, v95
	v_mul_f32_e32 v23, v27, v28
	v_mul_f32_e32 v23, v60, v23
	v_mul_f32_e32 v13, v22, v13
	v_mul_f32_e32 v22, v26, v28
	v_exp_f32_e32 v26, v23
	v_fmamk_f32 v23, v30, 0xbfb8aa3b, v95
	v_exp_f32_e32 v28, v23
	v_fmamk_f32 v15, v15, 0xbfb8aa3b, v93
	v_fma_f32 v14, -v26, v26, 1.0
	v_max_f32_e32 v14, 0, v14
	v_pk_add_f32 v[28:29], v[28:29], 1.0 op_sel_hi:[1,0]
	v_exp_f32_e32 v18, v18
	v_mul_f32_e32 v23, v28, v29
	v_exp_f32_e32 v19, v15
	v_sqrt_f32_e32 v14, v14
	v_rcp_f32_e32 v23, v23
	v_add_u32_e32 v127, 0x2000, v24
	v_add_u32_e32 v128, 0x2800, v24
	ds_write2_b64 v124, v[62:63], v[64:65] offset0:192 offset1:224
	ds_write2_b64 v127, v[50:51], v[6:7] offset0:64 offset1:96
	ds_write2_b64 v127, v[52:53], v[8:9] offset0:128 offset1:160
	ds_write2_b64 v127, v[56:57], v[20:21] offset0:192 offset1:224
	ds_write2_b64 v128, v[58:59], v[10:11] offset1:32
	v_lshl_add_u32 v125, v84, 3, s0
	v_pk_add_f32 v[18:19], v[18:19], 1.0 op_sel_hi:[1,0]
	s_waitcnt lgkmcnt(0)
; __device__ __forceinline__ unsigned cvt_pk_bf16(float lo, float hi) { unsigned r; asm volatile("v_cvt_pk_bf16_f32 %0, %1, %2" : "=v"(r) : "v"(lo), "v"(hi)); return r; }
; #define LAS __attribute__((address_space(3)))
; #define LDS_WAVE_SYNC() asm volatile("s_waitcnt lgkmcnt(0)" ::: "memory")
; template <int DIR, int MODE> ...
;     ...
;         LDS_WAVE_SYNC();
; #pragma unroll
;         for (int s = 0; s < 16; ++s) {
;             const int tt = DIR == 0 ? s : 15 - s, t = half * 16 + tt;
;             const f32x2 v = *(const LAS f32x2*)(au + (tt * 64 + lane) * 2);
;             hc = v.x * hc + v.y * xcr[t];
;             if (MODE == 0) { ap *= v.x;
;                 ((unsigned*)(a.ws + WS_HP))[((size_t)DIR * T + (size_t)b * SEQ + ch * 32 + t) * LW + c] = pg8::cvt_pk_bf16(hc, ap); }
	v_mul_f32_e32 v27, v22, v14
	v_mul_f32_e32 v14, v29, v23
	v_mul_f32_e32 v22, v28, v23
	v_mul_f32_e32 v23, v18, v19
	ds_read_b64 v[8:9], v125 offset:4608
	v_rcp_f32_e32 v23, v23
	v_mov_b32_e32 v84, v1
	v_mul_f32_e32 v14, v60, v14
	v_exp_f32_e32 v14, v14
	v_mul_f32_e32 v7, v18, v23
	s_waitcnt lgkmcnt(0)
	v_mul_f32_e32 v18, v85, v9
	v_mul_f32_e32 v6, v19, v23
	v_pk_fma_f32 v[18:19], v[84:85], v[8:9], v[18:19] op_sel_hi:[1,1,0]
	v_fma_f32 v15, -v14, v14, 1.0
	v_cvt_pk_bf16_f32 v19, v18, v8
	ds_read_b64 v[20:21], v125 offset:5120
	v_mul_f32_e32 v6, v60, v6
	v_max_f32_e32 v15, 0, v15
	v_exp_f32_e32 v6, v6
	v_fmamk_f32 v11, v16, 0xbfb8aa3b, v93
	global_store_dword v[122:123], v19, off
	v_mov_b32_e32 v19, v0
	s_waitcnt lgkmcnt(0)
	v_mul_f32_e32 v16, v0, v21
	v_sqrt_f32_e32 v15, v15
	v_pk_fma_f32 v[18:19], v[18:19], v[20:21], v[16:17] op_sel_hi:[1,1,0]
	v_pk_mul_f32 v[8:9], v[8:9], v[20:21]
	v_fma_f32 v10, -v6, v6, 1.0
	v_cvt_pk_bf16_f32 v16, v18, v8
	ds_read_b64 v[20:21], v125 offset:5632
	v_mul_f32_e32 v15, v22, v15
	v_max_f32_e32 v22, 0, v10
	v_fmamk_f32 v10, v32, 0xbfb8aa3b, v95
	v_exp_f32_e32 v10, v10
	v_exp_f32_e32 v11, v11
	global_store_dword v[120:121], v16, off offset:2048
	v_mov_b32_e32 v19, v130
	s_waitcnt lgkmcnt(0)
	v_mul_f32_e32 v16, v130, v21
	v_pk_fma_f32 v[18:19], v[18:19], v[20:21], v[16:17] op_sel_hi:[1,1,0]
	v_pk_mul_f32 v[8:9], v[8:9], v[20:21]
	v_pk_add_f32 v[10:11], v[10:11], 1.0 op_sel_hi:[1,0]
	v_cvt_pk_bf16_f32 v16, v18, v8
	ds_read_b64 v[20:21], v125 offset:6144
	v_mul_f32_e32 v19, v10, v11
	v_rcp_f32_e32 v23, v19
	global_store_dword v[116:117], v16, off offset:-4096
	v_mov_b32_e32 v19, v131
	s_waitcnt lgkmcnt(0)
	v_mul_f32_e32 v16, v131, v21
	v_pk_fma_f32 v[18:19], v[18:19], v[20:21], v[16:17] op_sel_hi:[1,1,0]
	v_pk_mul_f32 v[8:9], v[8:9], v[20:21]
	v_mov_b32_e32 v19, v132
	v_cvt_pk_bf16_f32 v16, v18, v8
	ds_read_b64 v[20:21], v125 offset:6656
	global_store_dword v[118:119], v16, off offset:2048
	v_sqrt_f32_e32 v22, v22
	v_mul_f32_e32 v11, v11, v23
	v_mul_f32_e32 v11, v60, v11
	s_waitcnt lgkmcnt(0)
	v_mul_f32_e32 v16, v132, v21
	v_pk_fma_f32 v[18:19], v[18:19], v[20:21], v[16:17] op_sel_hi:[1,1,0]
	v_pk_mul_f32 v[8:9], v[8:9], v[20:21]
	v_mul_f32_e32 v7, v7, v22
	v_cvt_pk_bf16_f32 v19, v18, v8
	ds_read_b64 v[20:21], v125 offset:7168
	global_store_dword v[116:117], v19, off
	v_mov_b32_e32 v19, v133
	v_exp_f32_e32 v16, v11
	v_fmac_f32_e32 v95, 0xbfb8aa3b, v33
	s_waitcnt lgkmcnt(0)
	v_mul_f32_e32 v22, v133, v21
	v_pk_fma_f32 v[18:19], v[18:19], v[20:21], v[22:23] op_sel_hi:[1,1,0]
	v_pk_mul_f32 v[8:9], v[8:9], v[20:21]
	v_mul_f32_e32 v23, v10, v23
	v_cvt_pk_bf16_f32 v11, v18, v8
	ds_read_b64 v[20:21], v125 offset:7680
	v_mov_b32_e32 v19, v134
	global_store_dword v[116:117], v11, off offset:2048
	v_fmac_f32_e32 v93, 0xbfb8aa3b, v17
	v_add_co_u32_e32 v110, vcc, s1, v88
	s_waitcnt lgkmcnt(0)
	v_mul_f32_e32 v10, v134, v21
	v_pk_fma_f32 v[10:11], v[18:19], v[20:21], v[10:11] op_sel_hi:[1,1,0]
	v_pk_mul_f32 v[8:9], v[8:9], v[20:21]
	v_exp_f32_e32 v20, v95
	v_cvt_pk_bf16_f32 v11, v10, v8
	ds_read_b64 v[18:19], v125 offset:8192
	global_store_dword v[112:113], v11, off offset:-4096
	v_mov_b32_e32 v11, v135
	v_exp_f32_e32 v21, v93
	v_addc_co_u32_e32 v111, vcc, 0, v89, vcc
	s_waitcnt lgkmcnt(0)
	v_mul_f32_e32 v22, v135, v19
	v_pk_fma_f32 v[10:11], v[10:11], v[18:19], v[22:23] op_sel_hi:[1,1,0]
	v_pk_mul_f32 v[8:9], v[8:9], v[18:19]
	v_pk_add_f32 v[20:21], v[20:21], 1.0 op_sel_hi:[1,0]
	v_cvt_pk_bf16_f32 v11, v10, v8
	ds_read_b64 v[18:19], v125 offset:8704
	global_store_dword v[114:115], v11, off offset:2048
	v_mov_b32_e32 v11, v136
	s_mov_b32 s1, 0x11f06000
	v_add_co_u32_e32 v108, vcc, s1, v88
	s_waitcnt lgkmcnt(0)
	v_mul_f32_e32 v22, v136, v19
	v_pk_fma_f32 v[10:11], v[10:11], v[18:19], v[22:23] op_sel_hi:[1,1,0]
	v_pk_mul_f32 v[8:9], v[8:9], v[18:19]
	v_addc_co_u32_e32 v109, vcc, 0, v89, vcc
	v_cvt_pk_bf16_f32 v11, v10, v8
	ds_read_b64 v[18:19], v125 offset:9216
	global_store_dword v[112:113], v11, off
	v_mov_b32_e32 v11, v137
	v_fma_f32 v24, -v16, v16, 1.0
	v_max_f32_e32 v17, 0, v24
	s_waitcnt lgkmcnt(0)
	v_mul_f32_e32 v22, v137, v19
	v_pk_fma_f32 v[10:11], v[10:11], v[18:19], v[22:23] op_sel_hi:[1,1,0]
	v_pk_mul_f32 v[8:9], v[8:9], v[18:19]
	v_mul_f32_e32 v22, v20, v21
	v_cvt_pk_bf16_f32 v11, v10, v8
	ds_read_b64 v[18:19], v125 offset:9728
	v_rcp_f32_e32 v25, v22
	global_store_dword v[112:113], v11, off offset:2048
	v_mov_b32_e32 v11, v138
	s_mov_b32 s1, 0x11f07000
	s_waitcnt lgkmcnt(0)
	v_mul_f32_e32 v22, v138, v19
	v_pk_fma_f32 v[10:11], v[10:11], v[18:19], v[22:23] op_sel_hi:[1,1,0]
	v_pk_mul_f32 v[8:9], v[8:9], v[18:19]
	v_mul_f32_e32 v21, v21, v25
	v_cvt_pk_bf16_f32 v11, v10, v8
	ds_read_b64 v[18:19], v125 offset:10240
	global_store_dword v[108:109], v11, off offset:-4096
	v_mov_b32_e32 v11, v139
	v_mul_f32_e32 v21, v60, v21
	v_add_co_u32_e32 v106, vcc, s1, v88
	s_waitcnt lgkmcnt(0)
	v_mul_f32_e32 v22, v139, v19
	v_pk_fma_f32 v[10:11], v[10:11], v[18:19], v[22:23] op_sel_hi:[1,1,0]
	v_pk_mul_f32 v[8:9], v[8:9], v[18:19]
	v_exp_f32_e32 v22, v21
	v_cvt_pk_bf16_f32 v11, v10, v8
	ds_read_b64 v[18:19], v125 offset:10752
	global_store_dword v[110:111], v11, off offset:2048
	v_mov_b32_e32 v11, v140
	v_fma_f32 v21, -v22, v22, 1.0
	v_max_f32_e32 v21, 0, v21
	s_waitcnt lgkmcnt(0)
	v_mul_f32_e32 v24, v140, v19
	v_pk_fma_f32 v[10:11], v[10:11], v[18:19], v[24:25] op_sel_hi:[1,1,0]
	v_pk_mul_f32 v[8:9], v[8:9], v[18:19]
	v_sqrt_f32_e32 v17, v17
	v_cvt_pk_bf16_f32 v11, v10, v8
	ds_read_b64 v[18:19], v125 offset:11264
	global_store_dword v[108:109], v11, off
	v_mov_b32_e32 v11, v141
	v_sqrt_f32_e32 v21, v21
	v_addc_co_u32_e32 v107, vcc, 0, v89, vcc
	s_waitcnt lgkmcnt(0)
; __device__ __forceinline__ unsigned cvt_pk_bf16(float lo, float hi) { unsigned r; asm volatile("v_cvt_pk_bf16_f32 %0, %1, %2" : "=v"(r) : "v"(lo), "v"(hi)); return r; }
; #define LAS __attribute__((address_space(3)))
; #define LDS_WAVE_SYNC() asm volatile("s_waitcnt lgkmcnt(0)" ::: "memory")
; template <int DIR, int MODE> ...
;     ...
; #pragma unroll
;     for (int hh = 0; hh < 2; ++hh) {
;         const int half = DIR == 0 ? hh : 1 - hh;
; #pragma unroll
;         for (int nt = 0; nt < 2; ++nt)
; #pragma unroll
;             for (int i = 0; i < 8; ++i) { const int tt = 8 * (i >> 2) + 4 * h + (i & 3);
;                 f32x2 v; v.x = accR[nt][8 * half + i]; v.y = accI[nt][8 * half + i];
;                 *(LAS f32x2*)(au + (tt * 64 + nt * 32 + r32) * 2) = v; }
;         LDS_WAVE_SYNC();
; #pragma unroll
;         for (int s = 0; s < 16; ++s) {
;             const int tt = DIR == 0 ? s : 15 - s, t = half * 16 + tt;
;             const f32x2 v = *(const LAS f32x2*)(au + (tt * 64 + lane) * 2);
;             hc = v.x * hc + v.y * xcr[t];
;             if (MODE == 0) { ap *= v.x;
;                 ((unsigned*)(a.ws + WS_HP))[((size_t)DIR * T + (size_t)b * SEQ + ch * 32 + t) * LW + c] = pg8::cvt_pk_bf16(hc, ap); }
;             if (MODE == 1) { if (DIR == 0) hf[t] = hc; else hf[t] = gl[t] * (hf[t] + hc); }
;         }
;         LDS_WAVE_SYNC();
	v_mul_f32_e32 v24, v141, v19
	v_pk_fma_f32 v[10:11], v[10:11], v[18:19], v[24:25] op_sel_hi:[1,1,0]
	v_pk_mul_f32 v[8:9], v[8:9], v[18:19]
	s_mov_b32 s1, 0x11f08000
	v_cvt_pk_bf16_f32 v11, v10, v8
	ds_read_b64 v[18:19], v125 offset:11776
	global_store_dword v[108:109], v11, off offset:2048
	v_mov_b32_e32 v11, v142
	v_add_co_u32_e32 v104, vcc, s1, v88
	s_waitcnt lgkmcnt(0)
	v_mul_f32_e32 v24, v142, v19
	v_pk_fma_f32 v[10:11], v[10:11], v[18:19], v[24:25] op_sel_hi:[1,1,0]
	v_pk_mul_f32 v[8:9], v[8:9], v[18:19]
	v_addc_co_u32_e32 v105, vcc, 0, v89, vcc
	v_cvt_pk_bf16_f32 v11, v10, v8
	ds_read_b64 v[18:19], v125 offset:12288
	v_mul_f32_e32 v20, v20, v25
	v_mul_f32_e32 v17, v23, v17
	v_mul_f32_e32 v23, v20, v21
	global_store_dword v[104:105], v11, off offset:-4096
	v_mov_b32_e32 v11, v143
	s_waitcnt lgkmcnt(0)
	v_mul_f32_e32 v20, v143, v19
	v_pk_fma_f32 v[10:11], v[10:11], v[18:19], v[20:21] op_sel_hi:[1,1,0]
	v_pk_mul_f32 v[8:9], v[8:9], v[18:19]
	v_mov_b32_e32 v97, v100
	v_cvt_pk_bf16_f32 v11, v10, v8
	global_store_dword v[106:107], v11, off offset:2048
	s_waitcnt lgkmcnt(0)
	ds_write2_b64 v124, v[34:35], v[2:3] offset0:64 offset1:96
	ds_write2_b64 v124, v[36:37], v[4:5] offset0:128 offset1:160
	ds_write2_b64 v124, v[38:39], v[12:13] offset0:192 offset1:224
	ds_write2_b64 v126, v[40:41], v[26:27] offset1:32
	ds_write2_b64 v127, v[42:43], v[14:15] offset0:64 offset1:96
	ds_write2_b64 v127, v[44:45], v[6:7] offset0:128 offset1:160
	ds_write2_b64 v127, v[46:47], v[16:17] offset0:192 offset1:224
	ds_write2_b64 v128, v[48:49], v[22:23] offset1:32
	s_waitcnt lgkmcnt(0)
	ds_read_b64 v[2:3], v125 offset:4608
	v_mov_b32_e32 v11, v144
	v_sub_f32_e32 v12, v98, v102
	v_pk_add_f32 v[4:5], v[96:97], v[102:103] neg_lo:[0,1] neg_hi:[0,1]
	s_mov_b32 s1, 0x11f0a000
	s_waitcnt lgkmcnt(0)
	v_mul_f32_e32 v6, v144, v3
	v_pk_fma_f32 v[6:7], v[10:11], v[2:3], v[6:7] op_sel_hi:[1,1,0]
	v_pk_mul_f32 v[2:3], v[8:9], v[2:3]
	v_sub_f32_e32 v10, v92, v12
	v_cvt_pk_bf16_f32 v7, v6, v2
	ds_read_b64 v[8:9], v125 offset:5120
	v_add_f32_e32 v14, v4, v10
	global_store_dword v[104:105], v7, off
	v_mov_b32_e32 v7, v145
	v_add_co_u32_e32 v10, vcc, s1, v88
	s_waitcnt lgkmcnt(0)
	v_mul_f32_e32 v4, v145, v9
	v_pk_fma_f32 v[6:7], v[6:7], v[8:9], v[4:5] op_sel_hi:[1,1,0]
	v_pk_mul_f32 v[2:3], v[2:3], v[8:9]
	v_mov_b32_e32 v7, v146
	v_cvt_pk_bf16_f32 v4, v6, v2
	ds_read_b64 v[8:9], v125 offset:5632
	global_store_dword v[104:105], v4, off offset:2048
	v_addc_co_u32_e32 v11, vcc, 0, v89, vcc
	s_mov_b32 s0, 0x11f09000
	s_waitcnt lgkmcnt(0)
	v_mul_f32_e32 v4, v146, v9
	v_pk_fma_f32 v[6:7], v[6:7], v[8:9], v[4:5] op_sel_hi:[1,1,0]
	v_pk_mul_f32 v[2:3], v[2:3], v[8:9]
	v_mov_b32_e32 v7, v147
	v_cvt_pk_bf16_f32 v4, v6, v2
	ds_read_b64 v[8:9], v125 offset:6144
	global_store_dword v[10:11], v4, off offset:-4096
	v_add_co_u32_e32 v12, vcc, s0, v88
	s_mov_b32 s1, 0x11f0c000
	s_waitcnt lgkmcnt(0)
	v_mul_f32_e32 v4, v147, v9
	v_pk_fma_f32 v[6:7], v[6:7], v[8:9], v[4:5] op_sel_hi:[1,1,0]
	v_pk_mul_f32 v[2:3], v[2:3], v[8:9]
	v_addc_co_u32_e32 v13, vcc, 0, v89, vcc
	v_cvt_pk_bf16_f32 v4, v6, v2
	ds_read_b64 v[8:9], v125 offset:6656
	global_store_dword v[12:13], v4, off offset:2048
	v_mov_b32_e32 v7, v148
	s_mov_b32 s0, 0x11f0b000
	s_waitcnt lgkmcnt(0)
	v_mul_f32_e32 v4, v148, v9
	v_pk_fma_f32 v[6:7], v[6:7], v[8:9], v[4:5] op_sel_hi:[1,1,0]
	v_pk_mul_f32 v[2:3], v[2:3], v[8:9]
	v_add_f32_e32 v5, v14, v5
	v_cvt_pk_bf16_f32 v4, v6, v2
	ds_read_b64 v[8:9], v125 offset:7168
	global_store_dword v[10:11], v4, off
	v_mov_b32_e32 v7, v149
	v_add_f32_e32 v12, v94, v5
	s_waitcnt lgkmcnt(0)
	v_mul_f32_e32 v4, v149, v9
	v_pk_fma_f32 v[4:5], v[6:7], v[8:9], v[4:5] op_sel_hi:[1,1,0]
	v_pk_mul_f32 v[2:3], v[2:3], v[8:9]
	s_nop 0
	v_cvt_pk_bf16_f32 v5, v4, v2
	ds_read_b64 v[6:7], v125 offset:7680
	global_store_dword v[10:11], v5, off offset:2048
	v_mov_b32_e32 v5, v150
	s_waitcnt lgkmcnt(0)
	v_mul_f32_e32 v8, v150, v7
	v_pk_fma_f32 v[4:5], v[4:5], v[6:7], v[8:9] op_sel_hi:[1,1,0]
	v_pk_mul_f32 v[2:3], v[2:3], v[6:7]
	v_add_co_u32_e32 v8, vcc, s1, v88
	v_cvt_pk_bf16_f32 v5, v4, v2
	ds_read_b64 v[6:7], v125 offset:8192
	s_nop 0
	v_addc_co_u32_e32 v9, vcc, 0, v89, vcc
	global_store_dword v[8:9], v5, off offset:-4096
	v_mov_b32_e32 v5, v151
	s_waitcnt lgkmcnt(0)
	v_mul_f32_e32 v10, v151, v7
	v_pk_fma_f32 v[4:5], v[4:5], v[6:7], v[10:11] op_sel_hi:[1,1,0]
	v_pk_mul_f32 v[2:3], v[2:3], v[6:7]
	v_add_co_u32_e32 v10, vcc, s0, v88
	v_cvt_pk_bf16_f32 v5, v4, v2
	ds_read_b64 v[6:7], v125 offset:8704
	s_nop 0
	v_addc_co_u32_e32 v11, vcc, 0, v89, vcc
	global_store_dword v[10:11], v5, off offset:2048
	v_mov_b32_e32 v5, v152
	s_waitcnt lgkmcnt(0)
	v_mul_f32_e32 v10, v152, v7
	v_pk_fma_f32 v[4:5], v[4:5], v[6:7], v[10:11] op_sel_hi:[1,1,0]
	v_pk_mul_f32 v[2:3], v[2:3], v[6:7]
	v_cmp_neq_f32_e32 vcc, s10, v163
	v_cvt_pk_bf16_f32 v5, v4, v2
	ds_read_b64 v[6:7], v125 offset:9216
	global_store_dword v[8:9], v5, off
	v_mov_b32_e32 v5, v153
	s_mov_b32 s1, 0x11f0e000
	v_cndmask_b32_e32 v14, v232, v12, vcc
	s_waitcnt lgkmcnt(0)
	v_mul_f32_e32 v10, v153, v7
	v_pk_fma_f32 v[4:5], v[4:5], v[6:7], v[10:11] op_sel_hi:[1,1,0]
	v_pk_mul_f32 v[2:3], v[2:3], v[6:7]
	s_mov_b32 s0, 0x11f0d000
	v_cvt_pk_bf16_f32 v5, v4, v2
	ds_read_b64 v[6:7], v125 offset:9728
	global_store_dword v[8:9], v5, off offset:2048
	v_mov_b32_e32 v5, v154
	s_waitcnt lgkmcnt(0)
	v_mul_f32_e32 v8, v154, v7
	v_pk_fma_f32 v[4:5], v[4:5], v[6:7], v[8:9] op_sel_hi:[1,1,0]
	v_pk_mul_f32 v[2:3], v[2:3], v[6:7]
	v_add_co_u32_e32 v8, vcc, s1, v88
	v_cvt_pk_bf16_f32 v5, v4, v2
	ds_read_b64 v[6:7], v125 offset:10240
	s_nop 0
	v_addc_co_u32_e32 v9, vcc, 0, v89, vcc
	global_store_dword v[8:9], v5, off offset:-4096
	v_mov_b32_e32 v5, v155
	s_waitcnt lgkmcnt(0)
; #define MFMA32(a, b, c) __builtin_amdgcn_mfma_f32_32x32x16_bf16((a), (b), (c), 0, 0, 0)
; template <int DIR, int MODE> ...
;     ...
;     for (int nt = 0; nt < 2; ++nt) {
; #pragma unroll
;         for (int i = 0; i < 16; ++i) { accR[nt][i] = 0.f; accI[nt][i] = 0.f; }
;         const bf16* wr_ = wl + (size_t)((DIR * 8 + w) * 2) * 4096 + (nt * 32 + r32) * 64 + 8 * h;
; #pragma unroll
;         for (int ks = 0; ks < 4; ++ks) {
;             const bf16x8 bR = *(const bf16x8*)(wr_ + 16 * ks), bI = *(const bf16x8*)(wr_ + 4096 + 16 * ks);
;             accR[nt] = MFMA32(af[ks], bR, accR[nt]); accI[nt] = MFMA32(af[ks], bI, accI[nt]); }
;     ...
;     if (MODE == 0) { f32x2 v; v.x = ap; v.y = hc; ((f32x2*)(a.ws + WS_TOT))[(size_t)((b * NCH + ch) * 2 + DIR) * LW + c] = v; }
	v_mul_f32_e32 v10, v155, v7
	v_pk_fma_f32 v[4:5], v[4:5], v[6:7], v[10:11] op_sel_hi:[1,1,0]
	v_pk_mul_f32 v[2:3], v[2:3], v[6:7]
	v_add_co_u32_e32 v10, vcc, s0, v88
	v_cvt_pk_bf16_f32 v5, v4, v2
	ds_read_b64 v[6:7], v125 offset:10752
	s_nop 0
	v_addc_co_u32_e32 v11, vcc, 0, v89, vcc
	global_store_dword v[10:11], v5, off offset:2048
	v_mov_b32_e32 v5, v156
	s_waitcnt lgkmcnt(0)
	v_mul_f32_e32 v10, v156, v7
	v_pk_fma_f32 v[4:5], v[4:5], v[6:7], v[10:11] op_sel_hi:[1,1,0]
	v_pk_mul_f32 v[2:3], v[2:3], v[6:7]
	s_mov_b32 s0, 0x11f0f000
	v_cvt_pk_bf16_f32 v5, v4, v2
	ds_read_b64 v[6:7], v125 offset:11264
	global_store_dword v[8:9], v5, off
	v_mov_b32_e32 v5, v157
	v_lshl_add_u64 v[10:11], s[42:43], 0, v[82:83]
	s_waitcnt lgkmcnt(0)
	v_mul_f32_e32 v12, v157, v7
	v_pk_fma_f32 v[4:5], v[4:5], v[6:7], v[12:13] op_sel_hi:[1,1,0]
	v_pk_mul_f32 v[2:3], v[2:3], v[6:7]
	v_add_co_u32_e32 v12, vcc, s0, v88
	v_cvt_pk_bf16_f32 v5, v4, v2
	ds_read_b64 v[6:7], v125 offset:11776
	global_store_dword v[8:9], v5, off offset:2048
	v_mov_b32_e32 v5, v158
	v_addc_co_u32_e32 v13, vcc, 0, v89, vcc
	s_waitcnt lgkmcnt(0)
	v_mul_f32_e32 v8, v158, v7
	v_pk_fma_f32 v[4:5], v[4:5], v[6:7], v[8:9] op_sel_hi:[1,1,0]
	v_pk_mul_f32 v[2:3], v[2:3], v[6:7]
	s_mov_b32 s0, 0x21000
	v_cvt_pk_bf16_f32 v5, v4, v2
	ds_read_b64 v[6:7], v125 offset:12288
	global_store_dword v[12:13], v5, off
	v_mov_b32_e32 v5, v87
	v_add_co_u32_e32 v98, vcc, s0, v90
	s_waitcnt lgkmcnt(0)
	v_mul_f32_e32 v8, v87, v7
	v_pk_mul_f32 v[2:3], v[2:3], v[6:7]
	v_pk_fma_f32 v[4:5], v[4:5], v[6:7], v[8:9] op_sel_hi:[1,1,0]
	v_addc_co_u32_e32 v99, vcc, 0, v91, vcc
	v_cvt_pk_bf16_f32 v3, v4, v2
	global_store_dword v[12:13], v3, off offset:2048
	v_mov_b32_e32 v3, v4
	s_waitcnt lgkmcnt(0)
	global_store_dwordx2 v[10:11], v[2:3], off
	global_load_dwordx4 v[2:5], v[98:99], off offset:-4096
	v_cmp_ngt_f32_e32 vcc, -1.0, v163
	v_mul_f32_e32 v6, 0xbfb8aa3b, v86
	s_mov_b32 s0, 0x23000
	v_cndmask_b32_e32 v10, v233, v14, vcc
	v_exp_f32_e32 v84, v6
	v_add_co_u32_e32 v122, vcc, s0, v90
	s_mov_b64 s[0:1], 0x20000
	s_nop 0
	v_addc_co_u32_e32 v123, vcc, 0, v91, vcc
	v_cmp_neq_f32_e32 vcc, -1.0, v163
	global_load_dwordx4 v[6:9], v[122:123], off offset:-4096
	global_load_dwordx4 v[106:109], v[98:99], off offset:96
	v_cndmask_b32_e32 v10, v234, v10, vcc
	v_cmp_lt_f32_e64 vcc, |v163|, s11
	v_lshl_add_u64 v[26:27], v[90:91], 0, s[0:1]
	s_mov_b32 s0, 0x22000
	v_cndmask_b32_e32 v100, v10, v163, vcc
	v_add_f32_e32 v22, 1.0, v84
	v_add_co_u32_e32 v30, vcc, s0, v90
	v_frexp_mant_f32_e32 v18, v22
	v_cvt_f64_f32_e32 v[14:15], v22
	v_addc_co_u32_e32 v31, vcc, 0, v91, vcc
	v_frexp_exp_i32_f64_e32 v19, v[14:15]
	v_cmp_gt_f32_e32 vcc, s6, v18
	v_add_f32_e32 v18, -1.0, v22
	v_sub_f32_e32 v24, v84, v18
	v_subbrev_co_u32_e32 v86, vcc, 0, v19, vcc
	v_sub_f32_e32 v19, v18, v22
	v_add_f32_e32 v23, 1.0, v19
	v_add_f32_e32 v23, v24, v23
	v_sub_u32_e32 v24, 0, v86
	v_ldexp_f32 v28, v22, v24
	global_load_dwordx4 v[10:13], v[26:27], off offset:32
	global_load_dwordx4 v[18:21], v[26:27], off offset:64
	v_add_f32_e32 v32, -1.0, v28
	v_add_f32_e32 v34, 1.0, v28
	v_add_f32_e32 v22, 1.0, v32
	v_add_f32_e32 v35, -1.0, v34
	v_ldexp_f32 v29, v23, v24
	v_sub_f32_e32 v33, v28, v22
	v_sub_f32_e32 v28, v28, v35
	v_add_f32_e32 v35, v29, v28
	v_add_f32_e32 v42, v34, v35
	v_rcp_f32_e32 v56, v42
	global_load_dwordx4 v[14:17], v[30:31], off offset:32
	v_add_f32_e32 v33, v29, v33
	v_sub_f32_e32 v34, v42, v34
	v_sub_f32_e32 v43, v35, v34
	v_add_f32_e32 v35, v32, v33
	v_mul_f32_e32 v101, v35, v56
	v_mul_f32_e32 v36, v42, v101
	v_fma_f32 v38, v101, v42, -v36
	v_fmac_f32_e32 v38, v101, v43
	v_add_f32_e32 v34, v36, v38
	v_sub_f32_e32 v37, v35, v34
	global_load_dwordx4 v[22:25], v[30:31], off offset:64
	v_sub_f32_e32 v32, v35, v32
	v_pk_add_f32 v[40:41], v[34:35], v[36:37] neg_lo:[0,1] neg_hi:[0,1]
	v_mov_b32_e32 v39, v34
	v_sub_f32_e32 v44, v33, v32
	v_pk_add_f32 v[34:35], v[40:41], v[38:39] neg_lo:[0,1] neg_hi:[0,1]
	global_load_dwordx4 v[26:29], v[26:27], off offset:96
	v_add_f32_e32 v35, v44, v35
	v_add_f32_e32 v34, v34, v35
	v_add_f32_e32 v35, v37, v34
	v_mul_f32_e32 v110, v56, v35
	v_mul_f32_e32 v50, v42, v110
	v_fma_f32 v52, v110, v42, -v50
	global_load_dwordx4 v[30:33], v[30:31], off offset:96
	v_fmac_f32_e32 v52, v110, v43
	global_load_dwordx4 v[90:93], v[98:99], off
	global_load_dwordx4 v[94:97], v[122:123], off
	v_sub_f32_e32 v36, v37, v35
	v_add_f32_e32 v57, v34, v36
	v_add_f32_e32 v34, v50, v52
	v_sub_f32_e32 v51, v35, v34
	v_pk_add_f32 v[54:55], v[34:35], v[50:51] neg_lo:[0,1] neg_hi:[0,1]
	v_mov_b32_e32 v53, v34
	s_waitcnt vmcnt(10)
	v_mfma_f32_32x32x16_bf16 v[34:49], v[70:73], v[2:5], 0
	v_add_f32_e64 v2, v54, -v52
	v_add_f32_e64 v3, v55, -v53
	global_load_dwordx4 v[102:105], v[98:99], off offset:32
	global_load_dwordx4 v[114:117], v[98:99], off offset:64
	v_add_f32_e32 v3, v57, v3
	v_add_f32_e32 v2, v2, v3
	v_add_f32_e32 v3, v101, v110
	v_sub_f32_e32 v4, v3, v101
	v_sub_f32_e32 v4, v110, v4
	global_load_dwordx4 v[110:113], v[122:123], off offset:32
	global_load_dwordx4 v[118:121], v[122:123], off offset:64
	global_load_dwordx4 v[164:167], v[122:123], off offset:96
	v_add_f32_e32 v2, v51, v2
	v_mul_f32_e32 v2, v56, v2
	v_add_f32_e32 v4, v4, v2
	s_waitcnt vmcnt(14)
	v_mfma_f32_32x32x16_bf16 v[50:65], v[70:73], v[6:9], 0
	v_add_f32_e32 v6, v3, v4
	v_mul_f32_e32 v7, v6, v6
	v_fmamk_f32 v2, v7, 0x3e9b6dac, v231
	v_fmaak_f32 v191, v7, v2, 0x3f2aaada
	v_cvt_f32_i32_e32 v2, v86
	v_sub_f32_e32 v3, v6, v3
	v_sub_f32_e32 v3, v4, v3
	v_ldexp_f32 v8, v3, 1
	v_mul_f32_e32 v3, v6, v7
	v_ldexp_f32 v5, v6, 1
	v_pk_mul_f32 v[6:7], v[2:3], v[190:191]
	s_waitcnt vmcnt(12)
; #define MFMA32(a, b, c) __builtin_amdgcn_mfma_f32_32x32x16_bf16((a), (b), (c), 0, 0, 0)
; template <int DIR, int MODE> ...
;     ...
;     for (int nt = 0; nt < 2; ++nt) {
; #pragma unroll
;         for (int i = 0; i < 16; ++i) { accR[nt][i] = 0.f; accI[nt][i] = 0.f; }
;         const bf16* wr_ = wl + (size_t)((DIR * 8 + w) * 2) * 4096 + (nt * 32 + r32) * 64 + 8 * h;
; #pragma unroll
;         for (int ks = 0; ks < 4; ++ks) {
;             const bf16x8 bR = *(const bf16x8*)(wr_ + 16 * ks), bI = *(const bf16x8*)(wr_ + 4096 + 16 * ks);
;             accR[nt] = MFMA32(af[ks], bR, accR[nt]); accI[nt] = MFMA32(af[ks], bI, accI[nt]); }
;     }
; #pragma unroll
;     for (int nt = 0; nt < 2; ++nt) {
;         const float nba = prm[DIR][nt][0], nbx = prm[DIR][nt][1], k8l = prm[DIR][nt][2];
; #pragma unroll
;         for (int i = 0; i < 16; ++i) {
;             const float d1 = 1.f + __builtin_amdgcn_exp2f(__builtin_fmaf(accR[nt][i], -1.4426950408889634f, nba));
;             const float d2 = 1.f + __builtin_amdgcn_exp2f(__builtin_fmaf(accI[nt][i], -1.4426950408889634f, nbx));
;             const float inv = __builtin_amdgcn_rcpf(d1 * d2), rr = inv * d2, ii = inv * d1;
;             const float av = __builtin_amdgcn_exp2f(k8l * rr);
;             accR[nt][i] = av; accI[nt][i] = __builtin_amdgcn_sqrtf(fmaxf(__builtin_fmaf(-av, av, 1.f), 0.f)) * ii; }
	v_mfma_f32_32x32x16_bf16 v[34:49], v[66:69], v[10:13], v[34:49]
	v_fma_f32 v4, v2, s7, -v6
	v_fmac_f32_e32 v4, 0xb102e308, v2
	v_add_f32_e64 v2, v6, v4
	v_add_f32_e64 v3, v7, v5
	v_cmp_neq_f32_e32 vcc, s10, v84
	v_sub_f32_e32 v5, v3, v5
	v_sub_f32_e32 v5, v7, v5
	v_add_f32_e32 v9, v8, v5
	v_mov_b32_e32 v8, v6
	v_pk_add_f32 v[6:7], v[2:3], v[6:7] neg_lo:[0,1] neg_hi:[0,1]
	v_pk_add_f32 v[10:11], v[2:3], v[8:9]
	s_waitcnt vmcnt(10)
	v_mfma_f32_32x32x16_bf16 v[50:65], v[66:69], v[14:17], v[50:65]
	v_mov_b32_e32 v7, v11
	v_mov_b32_e32 v5, v2
	v_mov_b32_e32 v8, v9
	v_mov_b32_e32 v9, v2
	s_mov_b32 s0, 0x13f0f000
	v_mfma_f32_32x32x16_bf16 v[34:49], v[78:81], v[18:21], v[34:49]
	v_add_f32_e64 v18, v4, -v6
	v_add_f32_e64 v19, v5, -v7
	v_add_f32_e64 v4, v4, v6
	v_add_f32_e64 v5, v5, v7
	v_add_f32_e64 v6, v5, -v2
	v_add_f32_e64 v7, v4, -v3
	v_pk_add_f32 v[12:13], v[10:11], v[6:7] op_sel_hi:[1,0] neg_lo:[0,1] neg_hi:[0,1]
	v_mov_b32_e32 v10, v11
	v_mov_b32_e32 v11, v5
	v_pk_mov_b32 v[6:7], v[2:3], v[6:7] op_sel:[1,0]
	v_mov_b32_e32 v12, v18
	v_pk_add_f32 v[6:7], v[10:11], v[6:7] neg_lo:[0,1] neg_hi:[0,1]
	s_waitcnt vmcnt(9)
	v_mfma_f32_32x32x16_bf16 v[50:65], v[78:81], v[22:25], v[50:65]
	v_add_f32_e64 v2, v8, -v6
	v_add_f32_e64 v3, v9, -v7
	v_mov_b32_e32 v19, v5
	v_add_f32_e64 v20, v12, v2
	v_add_f32_e64 v21, v13, v3
	v_pk_add_f32 v[6:7], v[20:21], v[20:21] op_sel:[0,1] op_sel_hi:[1,0]
	s_nop 0
	v_pk_add_f32 v[22:23], v[4:5], v[6:7] op_sel:[1,0] op_sel_hi:[0,1]
	v_mov_b32_e32 v21, v22
	v_pk_add_f32 v[24:25], v[20:21], v[18:19] neg_lo:[0,1] neg_hi:[0,1]
	v_mov_b32_e32 v3, v6
	v_sub_f32_e32 v19, v20, v24
	s_waitcnt vmcnt(8)
	v_mfma_f32_32x32x16_bf16 v[34:49], v[74:77], v[26:29], v[34:49]
	v_add_f32_e64 v26, v2, -v24
	v_add_f32_e64 v27, v3, -v25
	v_sub_f32_e32 v18, v18, v19
	v_add_f32_e32 v18, v26, v18
	v_add_f32_e32 v18, v18, v27
	v_add_f32_e32 v18, v22, v18
	v_cndmask_b32_e32 v86, v232, v18, vcc
	v_cmp_ngt_f32_e32 vcc, -1.0, v84
	s_waitcnt vmcnt(7)
	v_mfma_f32_32x32x16_bf16 v[50:65], v[74:77], v[30:33], v[50:65]
	s_waitcnt vmcnt(6)
	v_mfma_f32_32x32x16_bf16 v[2:17], v[70:73], v[90:93], 0
	s_waitcnt vmcnt(5)
	v_mfma_f32_32x32x16_bf16 v[18:33], v[70:73], v[94:97], 0
	v_cndmask_b32_e32 v70, v233, v86, vcc
	v_cmp_neq_f32_e32 vcc, -1.0, v84
	v_mul_f32_e32 v86, 0xbfb8aa3b, v159
	s_nop 0
	v_cndmask_b32_e32 v70, v234, v70, vcc
	v_cmp_lt_f32_e64 vcc, |v84|, s11
	s_waitcnt vmcnt(4)
	v_mfma_f32_32x32x16_bf16 v[2:17], v[66:69], v[102:105], v[2:17]
	v_cndmask_b32_e32 v98, v70, v84, vcc
	v_mul_f32_e32 v102, 0xbfb8aa3b, v160
	v_add_co_u32_e32 v96, vcc, s0, v88
	s_mov_b32 s0, 0x13f0e000
	s_nop 0
	v_addc_co_u32_e32 v97, vcc, 0, v89, vcc
	s_waitcnt vmcnt(2)
	v_mfma_f32_32x32x16_bf16 v[18:33], v[66:69], v[110:113], v[18:33]
	v_add_co_u32_e32 v94, vcc, s0, v88
	s_mov_b32 s0, 0x13f0d000
	s_nop 0
	v_addc_co_u32_e32 v95, vcc, 0, v89, vcc
	v_add_co_u32_e32 v92, vcc, s0, v88
	v_mfma_f32_32x32x16_bf16 v[2:17], v[78:81], v[114:117], v[2:17]
	s_nop 0
	v_addc_co_u32_e32 v93, vcc, 0, v89, vcc
	s_mov_b32 s0, 0x13f0c000
	v_add_co_u32_e32 v90, vcc, s0, v88
	s_mov_b32 s0, 0x13f0b000
	s_nop 0
	v_addc_co_u32_e32 v91, vcc, 0, v89, vcc
	s_waitcnt vmcnt(1)
	v_mfma_f32_32x32x16_bf16 v[18:33], v[78:81], v[118:121], v[18:33]
	v_mul_f32_e32 v80, 0xbfb8aa3b, v161
	v_mul_f32_e32 v81, 0xbfb8aa3b, v162
	v_fmamk_f32 v34, v34, 0xbfb8aa3b, v80
	v_exp_f32_e32 v78, v34
	v_fmamk_f32 v34, v50, 0xbfb8aa3b, v81
	v_exp_f32_e32 v79, v34
	v_fmamk_f32 v36, v36, 0xbfb8aa3b, v80
	v_exp_f32_e32 v50, v36
	v_fmamk_f32 v36, v52, 0xbfb8aa3b, v81
	v_pk_add_f32 v[78:79], v[78:79], 1.0 op_sel_hi:[1,0]
	v_mfma_f32_32x32x16_bf16 v[2:17], v[74:77], v[106:109], v[2:17]
	v_mul_f32_e32 v34, v78, v79
	v_rcp_f32_e32 v84, v34
	v_fmamk_f32 v34, v35, 0xbfb8aa3b, v80
	v_fmamk_f32 v35, v51, 0xbfb8aa3b, v81
	v_exp_f32_e32 v34, v34
	v_exp_f32_e32 v35, v35
	v_exp_f32_e32 v51, v36
	v_mul_f32_e32 v79, v79, v84
	v_mul_f32_e32 v78, v78, v84
	v_pk_add_f32 v[34:35], v[34:35], 1.0 op_sel_hi:[1,0]
	v_pk_add_f32 v[50:51], v[50:51], 1.0 op_sel_hi:[1,0]
	v_mul_f32_e32 v36, v34, v35
	v_rcp_f32_e32 v36, v36
	v_mul_f32_e32 v52, v50, v51
	v_rcp_f32_e32 v52, v52
	s_waitcnt vmcnt(0)
	v_mfma_f32_32x32x16_bf16 v[18:33], v[74:77], v[164:167], v[18:33]
	v_mul_f32_e32 v84, v35, v36
	v_mul_f32_e32 v99, v34, v36
	v_fmamk_f32 v34, v37, 0xbfb8aa3b, v80
	v_fmamk_f32 v35, v53, 0xbfb8aa3b, v81
	v_exp_f32_e32 v34, v34
	v_exp_f32_e32 v35, v35
	v_fmamk_f32 v36, v38, 0xbfb8aa3b, v80
	v_fmamk_f32 v37, v54, 0xbfb8aa3b, v81
	v_exp_f32_e32 v36, v36
	v_exp_f32_e32 v37, v37
	v_pk_add_f32 v[34:35], v[34:35], 1.0 op_sel_hi:[1,0]
	v_mul_f32_e32 v51, v51, v52
	v_mul_f32_e32 v38, v34, v35
	v_rcp_f32_e32 v38, v38
	v_pk_add_f32 v[36:37], v[36:37], 1.0 op_sel_hi:[1,0]
	v_mul_f32_e32 v50, v50, v52
	v_mul_f32_e32 v53, v36, v37
	v_rcp_f32_e32 v53, v53
	v_mul_f32_e32 v52, v35, v38
	v_mul_f32_e32 v54, v34, v38
	v_fmamk_f32 v34, v39, 0xbfb8aa3b, v80
	v_fmamk_f32 v35, v55, 0xbfb8aa3b, v81
	v_exp_f32_e32 v34, v34
	v_exp_f32_e32 v35, v35
	v_mul_f32_e32 v103, v37, v53
	v_fmamk_f32 v37, v40, 0xbfb8aa3b, v80
	v_exp_f32_e32 v38, v37
	v_fmamk_f32 v37, v56, 0xbfb8aa3b, v81
	v_pk_add_f32 v[34:35], v[34:35], 1.0 op_sel_hi:[1,0]
	v_exp_f32_e32 v39, v37
	v_mul_f32_e32 v37, v34, v35
	v_rcp_f32_e32 v37, v37
	v_mul_f32_e32 v53, v36, v53
	v_fmamk_f32 v36, v42, 0xbfb8aa3b, v80
	v_exp_f32_e32 v36, v36
	v_mul_f32_e32 v56, v35, v37
	v_mul_f32_e32 v104, v34, v37
	v_fmamk_f32 v34, v41, 0xbfb8aa3b, v80
	v_fmamk_f32 v35, v57, 0xbfb8aa3b, v81
	v_exp_f32_e32 v34, v34
	v_exp_f32_e32 v35, v35
	v_fmamk_f32 v37, v58, 0xbfb8aa3b, v81
	v_exp_f32_e32 v37, v37
	v_pk_add_f32 v[38:39], v[38:39], 1.0 op_sel_hi:[1,0]
; template <int DIR, int MODE> ...
;     ...
;     for (int nt = 0; nt < 2; ++nt) {
;         const float nba = prm[DIR][nt][0], nbx = prm[DIR][nt][1], k8l = prm[DIR][nt][2];
; #pragma unroll
;         for (int i = 0; i < 16; ++i) {
;             const float d1 = 1.f + __builtin_amdgcn_exp2f(__builtin_fmaf(accR[nt][i], -1.4426950408889634f, nba));
;             const float d2 = 1.f + __builtin_amdgcn_exp2f(__builtin_fmaf(accI[nt][i], -1.4426950408889634f, nbx));
;             const float inv = __builtin_amdgcn_rcpf(d1 * d2), rr = inv * d2, ii = inv * d1;
;             const float av = __builtin_amdgcn_exp2f(k8l * rr);
;             accR[nt][i] = av; accI[nt][i] = __builtin_amdgcn_sqrtf(fmaxf(__builtin_fmaf(-av, av, 1.f), 0.f)) * ii; }
	v_fmamk_f32 v44, v44, 0xbfb8aa3b, v80
	v_mul_f32_e32 v40, v38, v39
	v_rcp_f32_e32 v55, v40
	v_pk_add_f32 v[40:41], v[34:35], 1.0 op_sel_hi:[1,0]
	v_pk_add_f32 v[74:75], v[36:37], 1.0 op_sel_hi:[1,0]
	v_mul_f32_e32 v34, v40, v41
	v_rcp_f32_e32 v35, v34
	v_mul_f32_e32 v34, v74, v75
	v_rcp_f32_e32 v193, v34
	v_mov_b32_e32 v101, v75
	v_mul_f32_e32 v105, v39, v55
	v_mul_f32_e32 v57, v40, v35
	v_pk_mul_f32 v[76:77], v[100:101], v[192:193]
	v_mul_f32_e32 v42, v38, v55
	v_mul_f32_e32 v39, v76, v52
	v_exp_f32_e32 v40, v39
	v_mul_f32_e32 v38, v76, v51
	v_exp_f32_e32 v38, v38
	v_mul_f32_e32 v55, v41, v35
	v_fma_f32 v41, -v40, v40, 1.0
	v_max_f32_e32 v41, 0, v41
	v_mul_f32_e32 v51, v76, v56
	v_fma_f32 v39, -v38, v38, 1.0
	v_sqrt_f32_e32 v41, v41
	v_exp_f32_e32 v52, v51
	v_max_f32_e32 v39, 0, v39
	v_sqrt_f32_e32 v39, v39
	v_mul_f32_e32 v41, v54, v41
	v_fma_f32 v54, -v52, v52, 1.0
	v_max_f32_e32 v56, 0, v54
	v_mul_f32_e32 v54, v76, v105
	v_mul_f32_e32 v39, v50, v39
	v_mul_f32_e32 v50, v76, v103
	v_exp_f32_e32 v54, v54
	v_exp_f32_e32 v50, v50
	v_mul_f32_e32 v55, v76, v55
	v_sqrt_f32_e32 v58, v56
	v_exp_f32_e32 v56, v55
	v_fma_f32 v55, -v54, v54, 1.0
	v_fma_f32 v51, -v50, v50, 1.0
	v_max_f32_e32 v55, 0, v55
	v_max_f32_e32 v51, 0, v51
	v_sqrt_f32_e32 v55, v55
	v_sqrt_f32_e32 v51, v51
	v_fma_f32 v75, -v56, v56, 1.0
	v_max_f32_e32 v75, 0, v75
	v_mul_f32_e32 v55, v42, v55
	v_fmamk_f32 v42, v43, 0xbfb8aa3b, v80
	v_mul_f32_e32 v51, v53, v51
	v_mul_f32_e32 v53, v104, v58
	v_exp_f32_e32 v58, v42
	v_fmamk_f32 v42, v59, 0xbfb8aa3b, v81
	v_mul_f32_e32 v34, v76, v79
	v_sqrt_f32_e32 v75, v75
	v_exp_f32_e32 v59, v42
	v_exp_f32_e32 v34, v34
	v_mul_f32_e32 v42, v76, v77
	v_mul_f32_e32 v35, v76, v84
	v_mul_f32_e32 v57, v57, v75
	v_mul_f32_e32 v43, v74, v193
	v_exp_f32_e32 v42, v42
	v_pk_add_f32 v[74:75], v[58:59], 1.0 op_sel_hi:[1,0]
	v_exp_f32_e32 v36, v35
	v_fma_f32 v35, -v34, v34, 1.0
	v_mul_f32_e32 v58, v74, v75
	v_max_f32_e32 v35, 0, v35
	v_rcp_f32_e32 v59, v58
	v_sqrt_f32_e32 v35, v35
	v_fma_f32 v58, -v42, v42, 1.0
	v_max_f32_e32 v58, 0, v58
	v_sqrt_f32_e32 v77, v58
	v_mul_f32_e32 v58, v75, v59
	v_mul_f32_e32 v35, v78, v35
	v_mul_f32_e32 v58, v76, v58
	v_exp_f32_e32 v78, v44
	v_fmamk_f32 v44, v60, 0xbfb8aa3b, v81
	v_exp_f32_e32 v58, v58
	v_exp_f32_e32 v79, v44
	v_fmamk_f32 v45, v45, 0xbfb8aa3b, v80
	v_mul_f32_e32 v59, v74, v59
	v_fma_f32 v44, -v58, v58, 1.0
	v_pk_add_f32 v[78:79], v[78:79], 1.0 op_sel_hi:[1,0]
	v_max_f32_e32 v44, 0, v44
	v_mul_f32_e32 v60, v78, v79
	v_sqrt_f32_e32 v44, v44
	v_rcp_f32_e32 v75, v60
	v_exp_f32_e32 v60, v45
	v_fmamk_f32 v45, v61, 0xbfb8aa3b, v81
	v_exp_f32_e32 v61, v45
	v_mul_f32_e32 v59, v59, v44
	v_mul_f32_e32 v44, v79, v75
	v_mul_f32_e32 v44, v76, v44
	v_mul_f32_e32 v45, v78, v75
	v_exp_f32_e32 v44, v44
	v_pk_add_f32 v[74:75], v[60:61], 1.0 op_sel_hi:[1,0]
	v_fmamk_f32 v46, v46, 0xbfb8aa3b, v80
	v_mul_f32_e32 v60, v74, v75
	v_rcp_f32_e32 v61, v60
	v_fma_f32 v60, -v44, v44, 1.0
	v_max_f32_e32 v60, 0, v60
	v_mul_f32_e32 v43, v43, v77
	v_sqrt_f32_e32 v77, v60
	v_mul_f32_e32 v60, v75, v61
	v_exp_f32_e32 v78, v46
	v_fmamk_f32 v46, v62, 0xbfb8aa3b, v81
	v_mul_f32_e32 v60, v76, v60
	v_exp_f32_e32 v79, v46
	v_exp_f32_e32 v60, v60
	v_fmamk_f32 v47, v47, 0xbfb8aa3b, v80
	v_mul_f32_e32 v61, v74, v61
	v_pk_add_f32 v[78:79], v[78:79], 1.0 op_sel_hi:[1,0]
	v_fma_f32 v46, -v60, v60, 1.0
	v_mul_f32_e32 v62, v78, v79
	v_max_f32_e32 v46, 0, v46
	v_rcp_f32_e32 v75, v62
	v_exp_f32_e32 v62, v47
	v_fmamk_f32 v47, v63, 0xbfb8aa3b, v81
	v_sqrt_f32_e32 v46, v46
	v_exp_f32_e32 v63, v47
	v_mul_f32_e32 v47, v78, v75
	v_mul_f32_e32 v45, v45, v77
	v_mul_f32_e32 v61, v61, v46
	v_mul_f32_e32 v46, v79, v75
	v_pk_add_f32 v[62:63], v[62:63], 1.0 op_sel_hi:[1,0]
	v_mul_f32_e32 v46, v76, v46
	v_mul_f32_e32 v74, v62, v63
	v_exp_f32_e32 v46, v46
	v_rcp_f32_e32 v75, v74
	v_fmamk_f32 v48, v48, 0xbfb8aa3b, v80
	v_exp_f32_e32 v78, v48
	v_fma_f32 v74, -v46, v46, 1.0
	v_mul_f32_e32 v63, v63, v75
	v_max_f32_e32 v74, 0, v74
	v_mul_f32_e32 v63, v76, v63
	v_sqrt_f32_e32 v77, v74
	v_exp_f32_e32 v74, v63
	v_fmamk_f32 v48, v64, 0xbfb8aa3b, v81
	v_exp_f32_e32 v79, v48
	v_mul_f32_e32 v62, v62, v75
	v_fma_f32 v48, -v74, v74, 1.0
	v_max_f32_e32 v48, 0, v48
	v_sqrt_f32_e32 v48, v48
	v_pk_add_f32 v[78:79], v[78:79], 1.0 op_sel_hi:[1,0]
	v_fmac_f32_e32 v80, 0xbfb8aa3b, v49
	v_mul_f32_e32 v63, v78, v79
	v_fmac_f32_e32 v81, 0xbfb8aa3b, v65
	v_rcp_f32_e32 v63, v63
	v_mul_f32_e32 v75, v62, v48
	v_exp_f32_e32 v48, v80
	v_exp_f32_e32 v49, v81
	v_mul_f32_e32 v62, v79, v63
	v_mul_f32_e32 v62, v76, v62
	v_exp_f32_e32 v62, v62
	v_pk_add_f32 v[48:49], v[48:49], 1.0 op_sel_hi:[1,0]
	v_mul_f32_e32 v63, v78, v63
	v_mul_f32_e32 v64, v48, v49
	v_rcp_f32_e32 v65, v64
	v_fma_f32 v64, -v62, v62, 1.0
	v_max_f32_e32 v64, 0, v64
	v_sqrt_f32_e32 v78, v64
	v_mul_f32_e32 v49, v49, v65
	v_mul_f32_e32 v49, v76, v49
	v_exp_f32_e32 v64, v49
	v_fmamk_f32 v2, v2, 0xbfb8aa3b, v86
	v_exp_f32_e32 v76, v2
	v_fmamk_f32 v2, v18, 0xbfb8aa3b, v102
	v_mul_f32_e32 v47, v47, v77
	v_exp_f32_e32 v77, v2
	v_fma_f32 v2, -v64, v64, 1.0
	v_max_f32_e32 v2, 0, v2
	v_sqrt_f32_e32 v2, v2
	v_pk_add_f32 v[76:77], v[76:77], 1.0 op_sel_hi:[1,0]
	v_fmamk_f32 v4, v4, 0xbfb8aa3b, v86
	v_mul_f32_e32 v18, v76, v77
	v_rcp_f32_e32 v49, v18
	v_mul_f32_e32 v18, v48, v65
	v_mul_f32_e32 v65, v18, v2
	v_fmamk_f32 v2, v3, 0xbfb8aa3b, v86
	v_fmamk_f32 v3, v19, 0xbfb8aa3b, v102
	v_exp_f32_e32 v2, v2
	v_exp_f32_e32 v3, v3
	v_exp_f32_e32 v18, v4
	v_fmamk_f32 v4, v20, 0xbfb8aa3b, v102
	v_exp_f32_e32 v19, v4
	v_pk_add_f32 v[2:3], v[2:3], 1.0 op_sel_hi:[1,0]
	v_mul_f32_e32 v48, v77, v49
	v_mul_f32_e32 v4, v2, v3
	v_rcp_f32_e32 v4, v4
	v_mul_f32_e32 v49, v76, v49
; #define LAS __attribute__((address_space(3)))
; #define LDS_WAVE_SYNC() asm volatile("s_waitcnt lgkmcnt(0)" ::: "memory")
; template <int DIR, int MODE> ...
;     ...
;     for (int nt = 0; nt < 2; ++nt) {
;         const float nba = prm[DIR][nt][0], nbx = prm[DIR][nt][1], k8l = prm[DIR][nt][2];
; #pragma unroll
;         for (int i = 0; i < 16; ++i) {
;             const float d1 = 1.f + __builtin_amdgcn_exp2f(__builtin_fmaf(accR[nt][i], -1.4426950408889634f, nba));
;             const float d2 = 1.f + __builtin_amdgcn_exp2f(__builtin_fmaf(accI[nt][i], -1.4426950408889634f, nbx));
;             const float inv = __builtin_amdgcn_rcpf(d1 * d2), rr = inv * d2, ii = inv * d1;
;             const float av = __builtin_amdgcn_exp2f(k8l * rr);
;             accR[nt][i] = av; accI[nt][i] = __builtin_amdgcn_sqrtf(fmaxf(__builtin_fmaf(-av, av, 1.f), 0.f)) * ii; }
;     }
;     float hc = 0.f, ap = 1.f;
;     if (MODE == 1) hc = ((const float*)(a.ws + WS_CAR))[(size_t)((b * NCH + ch) * 2 + DIR) * LW + c];
; #pragma unroll
;     for (int hh = 0; hh < 2; ++hh) {
;         const int half = DIR == 0 ? hh : 1 - hh;
; #pragma unroll
;         for (int nt = 0; nt < 2; ++nt)
; #pragma unroll
;             for (int i = 0; i < 8; ++i) { const int tt = 8 * (i >> 2) + 4 * h + (i & 3);
;                 f32x2 v; v.x = accR[nt][8 * half + i]; v.y = accI[nt][8 * half + i];
;                 *(LAS f32x2*)(au + (tt * 64 + nt * 32 + r32) * 2) = v; }
;         LDS_WAVE_SYNC();
	v_pk_add_f32 v[18:19], v[18:19], 1.0 op_sel_hi:[1,0]
	v_mul_f32_e32 v63, v63, v78
	v_mul_f32_e32 v76, v3, v4
	v_mul_f32_e32 v77, v2, v4
	v_fmamk_f32 v2, v5, 0xbfb8aa3b, v86
	v_fmamk_f32 v3, v21, 0xbfb8aa3b, v102
	v_exp_f32_e32 v2, v2
	v_exp_f32_e32 v3, v3
	v_fmamk_f32 v4, v6, 0xbfb8aa3b, v86
	v_fmamk_f32 v5, v22, 0xbfb8aa3b, v102
	v_mul_f32_e32 v20, v18, v19
	v_exp_f32_e32 v4, v4
	v_exp_f32_e32 v5, v5
	v_pk_add_f32 v[2:3], v[2:3], 1.0 op_sel_hi:[1,0]
	v_rcp_f32_e32 v20, v20
	v_mul_f32_e32 v6, v2, v3
	v_rcp_f32_e32 v6, v6
	v_pk_add_f32 v[4:5], v[4:5], 1.0 op_sel_hi:[1,0]
	v_mul_f32_e32 v78, v19, v20
	v_mul_f32_e32 v19, v4, v5
	v_rcp_f32_e32 v19, v19
	v_mul_f32_e32 v80, v3, v6
	v_mul_f32_e32 v81, v2, v6
	v_fmamk_f32 v2, v7, 0xbfb8aa3b, v86
	v_fmamk_f32 v3, v23, 0xbfb8aa3b, v102
	v_exp_f32_e32 v2, v2
	v_exp_f32_e32 v3, v3
	v_mul_f32_e32 v84, v5, v19
	v_fmamk_f32 v5, v8, 0xbfb8aa3b, v86
	v_exp_f32_e32 v6, v5
	v_fmamk_f32 v5, v24, 0xbfb8aa3b, v102
	v_pk_add_f32 v[2:3], v[2:3], 1.0 op_sel_hi:[1,0]
	v_exp_f32_e32 v7, v5
	v_mul_f32_e32 v5, v2, v3
	v_rcp_f32_e32 v5, v5
	v_fma_f32 v37, -v36, v36, 1.0
	v_pk_add_f32 v[6:7], v[6:7], 1.0 op_sel_hi:[1,0]
	v_max_f32_e32 v37, 0, v37
	v_mul_f32_e32 v8, v6, v7
	v_mul_f32_e32 v101, v3, v5
	v_mul_f32_e32 v103, v2, v5
	v_fmamk_f32 v2, v10, 0xbfb8aa3b, v86
	v_fmamk_f32 v3, v26, 0xbfb8aa3b, v102
	v_rcp_f32_e32 v8, v8
	v_exp_f32_e32 v2, v2
	v_exp_f32_e32 v3, v3
	v_mul_f32_e32 v100, v4, v19
	v_mul_f32_e32 v104, v7, v8
	v_mul_f32_e32 v105, v6, v8
	v_fmamk_f32 v4, v9, 0xbfb8aa3b, v86
	v_pk_add_f32 v[8:9], v[2:3], 1.0 op_sel_hi:[1,0]
	v_sqrt_f32_e32 v37, v37
	v_mul_f32_e32 v2, v8, v9
	v_rcp_f32_e32 v193, v2
	v_fmamk_f32 v2, v25, 0xbfb8aa3b, v102
	v_exp_f32_e32 v4, v4
	v_exp_f32_e32 v5, v2
	v_mul_f32_e32 v37, v99, v37
	v_mov_b32_e32 v99, v9
	v_mul_f32_e32 v79, v18, v20
	v_pk_mul_f32 v[18:19], v[98:99], v[192:193]
	v_pk_add_f32 v[6:7], v[4:5], 1.0 op_sel_hi:[1,0]
	v_mul_f32_e32 v2, v18, v48
	v_exp_f32_e32 v2, v2
	v_mul_f32_e32 v3, v6, v7
	v_rcp_f32_e32 v3, v3
	v_mul_f32_e32 v9, v18, v19
	v_fma_f32 v4, -v2, v2, 1.0
	v_max_f32_e32 v4, 0, v4
	v_sqrt_f32_e32 v5, v4
	v_mul_f32_e32 v4, v18, v76
	v_mul_f32_e32 v76, v6, v3
	v_fmamk_f32 v6, v11, 0xbfb8aa3b, v86
	v_exp_f32_e32 v10, v6
	v_fmamk_f32 v6, v27, 0xbfb8aa3b, v102
	v_exp_f32_e32 v11, v6
	v_mul_f32_e32 v48, v7, v3
	v_exp_f32_e32 v20, v9
	v_mul_f32_e32 v8, v8, v193
	v_pk_add_f32 v[10:11], v[10:11], 1.0 op_sel_hi:[1,0]
	v_add_co_u32_e32 v72, vcc, s0, v88
	v_mul_f32_e32 v7, v10, v11
	v_rcp_f32_e32 v7, v7
	v_addc_co_u32_e32 v73, vcc, 0, v89, vcc
	s_mov_b32 s0, 0x13f0a000
	v_mul_f32_e32 v9, v11, v7
	v_mul_f32_e32 v9, v18, v9
	v_exp_f32_e32 v22, v9
	v_fma_f32 v9, -v20, v20, 1.0
	v_max_f32_e32 v9, 0, v9
	v_sqrt_f32_e32 v9, v9
	v_fma_f32 v11, -v22, v22, 1.0
	v_max_f32_e32 v11, 0, v11
	v_sqrt_f32_e32 v11, v11
	v_mul_f32_e32 v7, v10, v7
	v_mul_f32_e32 v21, v8, v9
	v_add_co_u32_e32 v70, vcc, s0, v88
	v_mul_f32_e32 v23, v7, v11
	v_fmamk_f32 v7, v12, 0xbfb8aa3b, v86
	v_exp_f32_e32 v8, v7
	v_fmamk_f32 v7, v28, 0xbfb8aa3b, v102
	v_exp_f32_e32 v9, v7
	v_fmamk_f32 v7, v13, 0xbfb8aa3b, v86
	v_exp_f32_e32 v10, v7
	v_fmamk_f32 v7, v29, 0xbfb8aa3b, v102
	v_exp_f32_e32 v11, v7
	v_pk_add_f32 v[8:9], v[8:9], 1.0 op_sel_hi:[1,0]
	v_addc_co_u32_e32 v71, vcc, 0, v89, vcc
	v_mul_f32_e32 v7, v8, v9
	v_rcp_f32_e32 v7, v7
	v_pk_add_f32 v[10:11], v[10:11], 1.0 op_sel_hi:[1,0]
	s_mov_b32 s0, 0x13f09000
	v_mul_f32_e32 v12, v10, v11
	v_rcp_f32_e32 v19, v12
	v_mul_f32_e32 v9, v9, v7
	v_mul_f32_e32 v9, v18, v9
	v_exp_f32_e32 v12, v9
	v_mul_f32_e32 v9, v11, v19
	v_mul_f32_e32 v9, v18, v9
	v_exp_f32_e32 v24, v9
	v_fma_f32 v9, -v12, v12, 1.0
	v_max_f32_e32 v9, 0, v9
	v_sqrt_f32_e32 v9, v9
	v_fma_f32 v11, -v24, v24, 1.0
	v_max_f32_e32 v11, 0, v11
	v_sqrt_f32_e32 v11, v11
	v_mul_f32_e32 v7, v8, v7
	v_mul_f32_e32 v13, v7, v9
	v_mul_f32_e32 v7, v10, v19
	v_mul_f32_e32 v25, v7, v11
	v_fmamk_f32 v7, v14, 0xbfb8aa3b, v86
	v_exp_f32_e32 v8, v7
	v_fmamk_f32 v7, v30, 0xbfb8aa3b, v102
	v_exp_f32_e32 v9, v7
	v_fmamk_f32 v7, v15, 0xbfb8aa3b, v86
	v_exp_f32_e32 v10, v7
	v_fmamk_f32 v7, v31, 0xbfb8aa3b, v102
	v_exp_f32_e32 v11, v7
	v_pk_add_f32 v[8:9], v[8:9], 1.0 op_sel_hi:[1,0]
	v_mul_f32_e32 v6, v18, v78
	v_mul_f32_e32 v7, v8, v9
	v_rcp_f32_e32 v7, v7
	v_pk_add_f32 v[10:11], v[10:11], 1.0 op_sel_hi:[1,0]
	v_add_co_u32_e32 v68, vcc, s0, v88
	v_mul_f32_e32 v14, v10, v11
	v_rcp_f32_e32 v19, v14
	v_mul_f32_e32 v9, v9, v7
	v_mul_f32_e32 v9, v18, v9
	v_exp_f32_e32 v14, v9
	v_mul_f32_e32 v9, v11, v19
	v_mul_f32_e32 v9, v18, v9
	v_exp_f32_e32 v26, v9
	v_fma_f32 v9, -v14, v14, 1.0
	v_max_f32_e32 v9, 0, v9
	v_sqrt_f32_e32 v9, v9
	v_fma_f32 v11, -v26, v26, 1.0
	v_max_f32_e32 v11, 0, v11
	v_sqrt_f32_e32 v11, v11
	v_mul_f32_e32 v7, v8, v7
	v_mul_f32_e32 v15, v7, v9
	v_mul_f32_e32 v7, v10, v19
	v_mul_f32_e32 v27, v7, v11
	v_fmamk_f32 v7, v16, 0xbfb8aa3b, v86
	v_exp_f32_e32 v8, v7
	v_fmamk_f32 v7, v32, 0xbfb8aa3b, v102
	v_exp_f32_e32 v9, v7
	v_fmac_f32_e32 v86, 0xbfb8aa3b, v17
	v_fmac_f32_e32 v102, 0xbfb8aa3b, v33
	v_exp_f32_e32 v10, v86
	v_exp_f32_e32 v11, v102
	v_pk_add_f32 v[8:9], v[8:9], 1.0 op_sel_hi:[1,0]
	v_mov_b32_e32 v86, v1
	v_mul_f32_e32 v7, v8, v9
	v_rcp_f32_e32 v7, v7
	v_pk_add_f32 v[10:11], v[10:11], 1.0 op_sel_hi:[1,0]
	v_addc_co_u32_e32 v69, vcc, 0, v89, vcc
	v_mul_f32_e32 v16, v10, v11
	v_rcp_f32_e32 v19, v16
	v_mul_f32_e32 v9, v9, v7
	v_mul_f32_e32 v9, v18, v9
	v_exp_f32_e32 v16, v9
	v_mul_f32_e32 v9, v11, v19
	v_mul_f32_e32 v9, v18, v9
	v_exp_f32_e32 v28, v9
	v_fma_f32 v9, -v16, v16, 1.0
	v_max_f32_e32 v9, 0, v9
	v_sqrt_f32_e32 v9, v9
	v_fma_f32 v11, -v28, v28, 1.0
	v_max_f32_e32 v11, 0, v11
	v_sqrt_f32_e32 v11, v11
	v_mul_f32_e32 v7, v8, v7
	v_mul_f32_e32 v17, v7, v9
	v_mul_f32_e32 v7, v10, v19
	v_mul_f32_e32 v29, v7, v11
	ds_write2_b64 v124, v[42:43], v[20:21] offset0:64 offset1:96
	ds_write2_b64 v124, v[58:59], v[22:23] offset0:128 offset1:160
	ds_write2_b64 v124, v[44:45], v[12:13] offset0:192 offset1:224
	ds_write2_b64 v126, v[60:61], v[24:25] offset1:32
	ds_write2_b64 v127, v[46:47], v[14:15] offset0:64 offset1:96
	ds_write2_b64 v127, v[74:75], v[26:27] offset0:128 offset1:160
	ds_write2_b64 v127, v[62:63], v[16:17] offset0:192 offset1:224
	ds_write2_b64 v128, v[64:65], v[28:29] offset1:32
	s_waitcnt lgkmcnt(0)
; __device__ __forceinline__ unsigned cvt_pk_bf16(float lo, float hi) { unsigned r; asm volatile("v_cvt_pk_bf16_f32 %0, %1, %2" : "=v"(r) : "v"(lo), "v"(hi)); return r; }
; #define LAS __attribute__((address_space(3)))
; #define LDS_WAVE_SYNC() asm volatile("s_waitcnt lgkmcnt(0)" ::: "memory")
; template <int DIR, int MODE> ...
;     ...
;             for (int i = 0; i < 8; ++i) { const int tt = 8 * (i >> 2) + 4 * h + (i & 3);
;                 f32x2 v; v.x = accR[nt][8 * half + i]; v.y = accI[nt][8 * half + i];
;                 *(LAS f32x2*)(au + (tt * 64 + nt * 32 + r32) * 2) = v; }
;         LDS_WAVE_SYNC();
; #pragma unroll
;         for (int s = 0; s < 16; ++s) {
;             const int tt = DIR == 0 ? s : 15 - s, t = half * 16 + tt;
;             const f32x2 v = *(const LAS f32x2*)(au + (tt * 64 + lane) * 2);
;             hc = v.x * hc + v.y * xcr[t];
;             if (MODE == 0) { ap *= v.x;
;                 ((unsigned*)(a.ws + WS_HP))[((size_t)DIR * T + (size_t)b * SEQ + ch * 32 + t) * LW + c] = pg8::cvt_pk_bf16(hc, ap); }
;             if (MODE == 1) { if (DIR == 0) hf[t] = hc; else hf[t] = gl[t] * (hf[t] + hc); }
;         }
	ds_read_b64 v[8:9], v125 offset:12288
	v_mul_f32_e32 v10, v18, v80
	v_exp_f32_e32 v10, v10
	v_mul_f32_e32 v19, v18, v101
	v_exp_f32_e32 v4, v4
	s_waitcnt lgkmcnt(0)
	v_mul_f32_e32 v12, v87, v9
	v_pk_fma_f32 v[12:13], v[86:87], v[8:9], v[12:13] op_sel_hi:[1,1,0]
	v_fma_f32 v17, -v10, v10, 1.0
	v_cvt_pk_bf16_f32 v11, v12, v8
	ds_read_b64 v[14:15], v125 offset:11776
	v_mov_b32_e32 v13, v158
	global_store_dword v[96:97], v11, off offset:2048
	v_exp_f32_e32 v6, v6
	s_mov_b32 s0, 0x13f08000
	s_waitcnt lgkmcnt(0)
	v_mul_f32_e32 v16, v158, v15
	v_pk_fma_f32 v[12:13], v[12:13], v[14:15], v[16:17] op_sel_hi:[1,1,0]
	v_pk_mul_f32 v[8:9], v[8:9], v[14:15]
	v_max_f32_e32 v13, 0, v17
	v_cvt_pk_bf16_f32 v11, v12, v8
	ds_read_b64 v[14:15], v125 offset:11264
	v_sqrt_f32_e32 v17, v13
	v_mov_b32_e32 v13, v157
	global_store_dword v[96:97], v11, off
	v_mul_f32_e32 v3, v49, v5
	s_waitcnt lgkmcnt(0)
	v_mul_f32_e32 v16, v157, v15
	v_pk_fma_f32 v[12:13], v[12:13], v[14:15], v[16:17] op_sel_hi:[1,1,0]
	v_pk_mul_f32 v[8:9], v[8:9], v[14:15]
	v_fma_f32 v5, -v4, v4, 1.0
	v_cvt_pk_bf16_f32 v13, v12, v8
	ds_read_b64 v[14:15], v125 offset:10752
	global_store_dword v[94:95], v13, off offset:2048
	v_mov_b32_e32 v13, v156
	v_fma_f32 v49, -v6, v6, 1.0
	v_mul_f32_e32 v11, v81, v17
	s_waitcnt lgkmcnt(0)
	v_mul_f32_e32 v16, v156, v15
	v_pk_fma_f32 v[12:13], v[12:13], v[14:15], v[16:17] op_sel_hi:[1,1,0]
	v_pk_mul_f32 v[8:9], v[8:9], v[14:15]
	v_mul_f32_e32 v16, v18, v84
	v_cvt_pk_bf16_f32 v13, v12, v8
	ds_read_b64 v[14:15], v125 offset:10240
	global_store_dword v[94:95], v13, off
	v_mov_b32_e32 v13, v155
	v_exp_f32_e32 v16, v16
	v_add_co_u32_e32 v66, vcc, s0, v88
	s_waitcnt lgkmcnt(0)
	v_mul_f32_e32 v20, v155, v15
	v_pk_fma_f32 v[12:13], v[12:13], v[14:15], v[20:21] op_sel_hi:[1,1,0]
	v_pk_mul_f32 v[8:9], v[8:9], v[14:15]
	v_fma_f32 v17, -v16, v16, 1.0
	v_cvt_pk_bf16_f32 v13, v12, v8
	ds_read_b64 v[14:15], v125 offset:9728
	global_store_dword v[92:93], v13, off offset:2048
	v_mov_b32_e32 v13, v154
	v_max_f32_e32 v5, 0, v5
	v_max_f32_e32 v7, 0, v49
	s_waitcnt lgkmcnt(0)
	v_mul_f32_e32 v20, v154, v15
	v_pk_fma_f32 v[12:13], v[12:13], v[14:15], v[20:21] op_sel_hi:[1,1,0]
	v_pk_mul_f32 v[8:9], v[8:9], v[14:15]
	v_exp_f32_e32 v20, v19
	v_cvt_pk_bf16_f32 v13, v12, v8
	ds_read_b64 v[14:15], v125 offset:9216
	global_store_dword v[92:93], v13, off
	v_mov_b32_e32 v13, v153
	v_fma_f32 v19, -v20, v20, 1.0
	v_max_f32_e32 v19, 0, v19
	s_waitcnt lgkmcnt(0)
	v_mul_f32_e32 v22, v153, v15
	v_pk_fma_f32 v[12:13], v[12:13], v[14:15], v[22:23] op_sel_hi:[1,1,0]
	v_pk_mul_f32 v[8:9], v[8:9], v[14:15]
	v_sqrt_f32_e32 v19, v19
	v_cvt_pk_bf16_f32 v13, v12, v8
	ds_read_b64 v[14:15], v125 offset:8704
	global_store_dword v[90:91], v13, off offset:2048
	v_mov_b32_e32 v13, v152
	v_mul_f32_e32 v21, v103, v19
	v_mul_f32_e32 v19, v18, v104
	s_waitcnt lgkmcnt(0)
	v_mul_f32_e32 v22, v152, v15
	v_pk_fma_f32 v[12:13], v[12:13], v[14:15], v[22:23] op_sel_hi:[1,1,0]
	v_pk_mul_f32 v[8:9], v[8:9], v[14:15]
	v_mul_f32_e32 v18, v18, v48
	v_cvt_pk_bf16_f32 v13, v12, v8
	ds_read_b64 v[14:15], v125 offset:8192
	global_store_dword v[90:91], v13, off
	v_mov_b32_e32 v13, v151
	v_exp_f32_e32 v18, v18
	v_max_f32_e32 v17, 0, v17
	s_waitcnt lgkmcnt(0)
	v_mul_f32_e32 v22, v151, v15
	v_pk_fma_f32 v[12:13], v[12:13], v[14:15], v[22:23] op_sel_hi:[1,1,0]
	v_pk_mul_f32 v[8:9], v[8:9], v[14:15]
	v_addc_co_u32_e32 v67, vcc, 0, v89, vcc
	v_cvt_pk_bf16_f32 v13, v12, v8
	ds_read_b64 v[14:15], v125 offset:7680
	global_store_dword v[72:73], v13, off offset:2048
	v_mov_b32_e32 v13, v150
	v_sqrt_f32_e32 v5, v5
	v_sqrt_f32_e32 v7, v7
	s_waitcnt lgkmcnt(0)
	v_mul_f32_e32 v22, v150, v15
	v_pk_fma_f32 v[12:13], v[12:13], v[14:15], v[22:23] op_sel_hi:[1,1,0]
	v_pk_mul_f32 v[8:9], v[8:9], v[14:15]
	v_fma_f32 v23, -v18, v18, 1.0
	v_cvt_pk_bf16_f32 v13, v12, v8
	ds_read_b64 v[14:15], v125 offset:7168
	global_store_dword v[72:73], v13, off
	v_mov_b32_e32 v13, v149
	v_max_f32_e32 v23, 0, v23
	v_exp_f32_e32 v22, v19
	s_waitcnt lgkmcnt(0)
	v_mul_f32_e32 v24, v149, v15
	v_pk_fma_f32 v[12:13], v[12:13], v[14:15], v[24:25] op_sel_hi:[1,1,0]
	v_pk_mul_f32 v[8:9], v[8:9], v[14:15]
	v_fma_f32 v19, -v22, v22, 1.0
	v_cvt_pk_bf16_f32 v13, v12, v8
	ds_read_b64 v[14:15], v125 offset:6656
	global_store_dword v[70:71], v13, off offset:2048
	v_mov_b32_e32 v13, v148
	v_max_f32_e32 v19, 0, v19
	v_sqrt_f32_e32 v17, v17
	s_waitcnt lgkmcnt(0)
	v_mul_f32_e32 v24, v148, v15
	v_pk_fma_f32 v[12:13], v[12:13], v[14:15], v[24:25] op_sel_hi:[1,1,0]
	v_pk_mul_f32 v[8:9], v[8:9], v[14:15]
	v_sqrt_f32_e32 v19, v19
	v_cvt_pk_bf16_f32 v13, v12, v8
	ds_read_b64 v[14:15], v125 offset:6144
	global_store_dword v[70:71], v13, off
	v_mov_b32_e32 v13, v147
	v_mul_f32_e32 v5, v77, v5
	v_mul_f32_e32 v7, v79, v7
	s_waitcnt lgkmcnt(0)
	v_mul_f32_e32 v24, v147, v15
	v_pk_fma_f32 v[12:13], v[12:13], v[14:15], v[24:25] op_sel_hi:[1,1,0]
	v_pk_mul_f32 v[8:9], v[8:9], v[14:15]
	v_mul_f32_e32 v17, v100, v17
	v_cvt_pk_bf16_f32 v13, v12, v8
	ds_read_b64 v[14:15], v125 offset:5632
	global_store_dword v[68:69], v13, off offset:2048
	v_mov_b32_e32 v13, v146
	s_mov_b32 s0, 0x13f07000
	s_waitcnt lgkmcnt(0)
	v_mul_f32_e32 v24, v146, v15
	v_pk_fma_f32 v[12:13], v[12:13], v[14:15], v[24:25] op_sel_hi:[1,1,0]
	v_pk_mul_f32 v[8:9], v[8:9], v[14:15]
	v_sqrt_f32_e32 v25, v23
	v_cvt_pk_bf16_f32 v13, v12, v8
	ds_read_b64 v[14:15], v125 offset:5120
	global_store_dword v[68:69], v13, off
	v_mov_b32_e32 v13, v145
	v_mul_f32_e32 v23, v105, v19
	v_mul_f32_e32 v19, v76, v25
	s_waitcnt lgkmcnt(0)
; __device__ __forceinline__ unsigned cvt_pk_bf16(float lo, float hi) { unsigned r; asm volatile("v_cvt_pk_bf16_f32 %0, %1, %2" : "=v"(r) : "v"(lo), "v"(hi)); return r; }
; #define LAS __attribute__((address_space(3)))
; #define LDS_WAVE_SYNC() asm volatile("s_waitcnt lgkmcnt(0)" ::: "memory")
; template <int DIR, int MODE> ...
;     ...
;     for (int hh = 0; hh < 2; ++hh) {
;         const int half = DIR == 0 ? hh : 1 - hh;
; #pragma unroll
;         for (int nt = 0; nt < 2; ++nt)
; #pragma unroll
;             for (int i = 0; i < 8; ++i) { const int tt = 8 * (i >> 2) + 4 * h + (i & 3);
;                 f32x2 v; v.x = accR[nt][8 * half + i]; v.y = accI[nt][8 * half + i];
;                 *(LAS f32x2*)(au + (tt * 64 + nt * 32 + r32) * 2) = v; }
;         LDS_WAVE_SYNC();
; #pragma unroll
;         for (int s = 0; s < 16; ++s) {
;             const int tt = DIR == 0 ? s : 15 - s, t = half * 16 + tt;
;             const f32x2 v = *(const LAS f32x2*)(au + (tt * 64 + lane) * 2);
;             hc = v.x * hc + v.y * xcr[t];
;             if (MODE == 0) { ap *= v.x;
;                 ((unsigned*)(a.ws + WS_HP))[((size_t)DIR * T + (size_t)b * SEQ + ch * 32 + t) * LW + c] = pg8::cvt_pk_bf16(hc, ap); }
;             if (MODE == 1) { if (DIR == 0) hf[t] = hc; else hf[t] = gl[t] * (hf[t] + hc); }
;         }
;         LDS_WAVE_SYNC();
;     }
;     if (MODE == 0) { f32x2 v; v.x = ap; v.y = hc; ((f32x2*)(a.ws + WS_TOT))[(size_t)((b * NCH + ch) * 2 + DIR) * LW + c] = v; }
	v_mul_f32_e32 v24, v145, v15
	v_pk_fma_f32 v[12:13], v[12:13], v[14:15], v[24:25] op_sel_hi:[1,1,0]
	v_pk_mul_f32 v[8:9], v[8:9], v[14:15]
	s_nop 0
	v_cvt_pk_bf16_f32 v13, v12, v8
	ds_read_b64 v[14:15], v125 offset:4608
	global_store_dword v[66:67], v13, off offset:2048
	v_mov_b32_e32 v13, v144
	s_waitcnt lgkmcnt(0)
	v_mul_f32_e32 v24, v144, v15
	v_pk_fma_f32 v[12:13], v[12:13], v[14:15], v[24:25] op_sel_hi:[1,1,0]
	v_pk_mul_f32 v[8:9], v[8:9], v[14:15]
	s_nop 0
	v_cvt_pk_bf16_f32 v13, v12, v8
	global_store_dword v[66:67], v13, off
	s_waitcnt lgkmcnt(0)
	ds_write2_b64 v124, v[34:35], v[2:3] offset0:64 offset1:96
	ds_write2_b64 v124, v[36:37], v[4:5] offset0:128 offset1:160
	ds_write2_b64 v124, v[38:39], v[6:7] offset0:192 offset1:224
	ds_write2_b64 v126, v[40:41], v[10:11] offset1:32
	ds_write2_b64 v127, v[50:51], v[16:17] offset0:64 offset1:96
	ds_write2_b64 v127, v[52:53], v[20:21] offset0:128 offset1:160
	ds_write2_b64 v127, v[54:55], v[22:23] offset0:192 offset1:224
	ds_write2_b64 v128, v[56:57], v[18:19] offset1:32
	s_waitcnt lgkmcnt(0)
	ds_read_b64 v[2:3], v125 offset:12288
	v_mov_b32_e32 v13, v143
	s_waitcnt lgkmcnt(0)
	v_mul_f32_e32 v4, v143, v3
	v_pk_fma_f32 v[4:5], v[12:13], v[2:3], v[4:5] op_sel_hi:[1,1,0]
	v_pk_mul_f32 v[2:3], v[8:9], v[2:3]
	v_add_co_u32_e32 v8, vcc, s0, v88
	v_cvt_pk_bf16_f32 v5, v4, v2
	ds_read_b64 v[6:7], v125 offset:11776
	s_nop 0
	v_addc_co_u32_e32 v9, vcc, 0, v89, vcc
	global_store_dword v[8:9], v5, off offset:2048
	v_mov_b32_e32 v5, v142
	s_waitcnt lgkmcnt(0)
	v_mul_f32_e32 v10, v142, v7
	v_pk_fma_f32 v[4:5], v[4:5], v[6:7], v[10:11] op_sel_hi:[1,1,0]
	v_pk_mul_f32 v[2:3], v[2:3], v[6:7]
	s_mov_b32 s0, 0x13f06000
	v_cvt_pk_bf16_f32 v5, v4, v2
	ds_read_b64 v[6:7], v125 offset:11264
	global_store_dword v[8:9], v5, off
	v_mov_b32_e32 v5, v141
	v_lshl_add_u64 v[12:13], s[40:41], 0, v[82:83]
	s_waitcnt lgkmcnt(0)
	v_mul_f32_e32 v8, v141, v7
	v_pk_fma_f32 v[4:5], v[4:5], v[6:7], v[8:9] op_sel_hi:[1,1,0]
	v_pk_mul_f32 v[2:3], v[2:3], v[6:7]
	v_add_co_u32_e32 v8, vcc, s0, v88
	v_cvt_pk_bf16_f32 v5, v4, v2
	ds_read_b64 v[6:7], v125 offset:10752
	s_nop 0
	v_addc_co_u32_e32 v9, vcc, 0, v89, vcc
	global_store_dword v[8:9], v5, off offset:2048
	v_mov_b32_e32 v5, v140
	s_waitcnt lgkmcnt(0)
	v_mul_f32_e32 v10, v140, v7
	v_pk_fma_f32 v[4:5], v[4:5], v[6:7], v[10:11] op_sel_hi:[1,1,0]
	v_pk_mul_f32 v[2:3], v[2:3], v[6:7]
	s_mov_b32 s0, 0x13f05000
	v_cvt_pk_bf16_f32 v5, v4, v2
	ds_read_b64 v[6:7], v125 offset:10240
	global_store_dword v[8:9], v5, off
	v_mov_b32_e32 v5, v139
	s_waitcnt lgkmcnt(0)
	v_mul_f32_e32 v8, v139, v7
	v_pk_fma_f32 v[4:5], v[4:5], v[6:7], v[8:9] op_sel_hi:[1,1,0]
	v_pk_mul_f32 v[2:3], v[2:3], v[6:7]
	v_add_co_u32_e32 v8, vcc, s0, v88
	v_cvt_pk_bf16_f32 v5, v4, v2
	ds_read_b64 v[6:7], v125 offset:9728
	s_nop 0
	v_addc_co_u32_e32 v9, vcc, 0, v89, vcc
	global_store_dword v[8:9], v5, off offset:2048
	v_mov_b32_e32 v5, v138
	s_waitcnt lgkmcnt(0)
	v_mul_f32_e32 v10, v138, v7
	v_pk_fma_f32 v[4:5], v[4:5], v[6:7], v[10:11] op_sel_hi:[1,1,0]
	v_pk_mul_f32 v[2:3], v[2:3], v[6:7]
	s_mov_b32 s0, 0x13f04000
	v_cvt_pk_bf16_f32 v5, v4, v2
	ds_read_b64 v[6:7], v125 offset:9216
	global_store_dword v[8:9], v5, off
	v_mov_b32_e32 v5, v137
	s_waitcnt lgkmcnt(0)
	v_mul_f32_e32 v8, v137, v7
	v_pk_fma_f32 v[4:5], v[4:5], v[6:7], v[8:9] op_sel_hi:[1,1,0]
	v_pk_mul_f32 v[2:3], v[2:3], v[6:7]
	v_add_co_u32_e32 v8, vcc, s0, v88
	v_cvt_pk_bf16_f32 v5, v4, v2
	ds_read_b64 v[6:7], v125 offset:8704
	s_nop 0
	v_addc_co_u32_e32 v9, vcc, 0, v89, vcc
	global_store_dword v[8:9], v5, off offset:2048
	v_mov_b32_e32 v5, v136
	s_waitcnt lgkmcnt(0)
	v_mul_f32_e32 v10, v136, v7
	v_pk_fma_f32 v[4:5], v[4:5], v[6:7], v[10:11] op_sel_hi:[1,1,0]
	v_pk_mul_f32 v[2:3], v[2:3], v[6:7]
	s_mov_b32 s0, 0x13f03000
	v_cvt_pk_bf16_f32 v5, v4, v2
	ds_read_b64 v[6:7], v125 offset:8192
	global_store_dword v[8:9], v5, off
	v_mov_b32_e32 v5, v135
	s_waitcnt lgkmcnt(0)
	v_mul_f32_e32 v8, v135, v7
	v_pk_fma_f32 v[4:5], v[4:5], v[6:7], v[8:9] op_sel_hi:[1,1,0]
	v_pk_mul_f32 v[2:3], v[2:3], v[6:7]
	v_add_co_u32_e32 v8, vcc, s0, v88
	v_cvt_pk_bf16_f32 v5, v4, v2
	ds_read_b64 v[6:7], v125 offset:7680
	s_nop 0
	v_addc_co_u32_e32 v9, vcc, 0, v89, vcc
	global_store_dword v[8:9], v5, off offset:2048
	v_mov_b32_e32 v5, v134
	s_waitcnt lgkmcnt(0)
	v_mul_f32_e32 v10, v134, v7
	v_pk_fma_f32 v[4:5], v[4:5], v[6:7], v[10:11] op_sel_hi:[1,1,0]
	v_pk_mul_f32 v[2:3], v[2:3], v[6:7]
	s_mov_b32 s0, 0x13f02000
	v_cvt_pk_bf16_f32 v5, v4, v2
	ds_read_b64 v[6:7], v125 offset:7168
	global_store_dword v[8:9], v5, off
	v_mov_b32_e32 v5, v133
	s_waitcnt lgkmcnt(0)
	v_mul_f32_e32 v8, v133, v7
	v_pk_fma_f32 v[4:5], v[4:5], v[6:7], v[8:9] op_sel_hi:[1,1,0]
	v_pk_mul_f32 v[2:3], v[2:3], v[6:7]
	v_add_co_u32_e32 v8, vcc, s0, v88
	v_cvt_pk_bf16_f32 v5, v4, v2
	ds_read_b64 v[6:7], v125 offset:6656
	s_nop 0
	v_addc_co_u32_e32 v9, vcc, 0, v89, vcc
	global_store_dword v[8:9], v5, off offset:2048
	v_mov_b32_e32 v5, v132
	s_waitcnt lgkmcnt(0)
	v_mul_f32_e32 v10, v132, v7
	v_pk_fma_f32 v[4:5], v[4:5], v[6:7], v[10:11] op_sel_hi:[1,1,0]
	v_pk_mul_f32 v[2:3], v[2:3], v[6:7]
	s_mov_b32 s0, 0x13f01000
	v_cvt_pk_bf16_f32 v5, v4, v2
	ds_read_b64 v[6:7], v125 offset:6144
	global_store_dword v[8:9], v5, off
	v_mov_b32_e32 v5, v131
	v_add_co_u32_e32 v10, vcc, s0, v88
	s_waitcnt lgkmcnt(0)
	v_mul_f32_e32 v8, v131, v7
	v_pk_fma_f32 v[4:5], v[4:5], v[6:7], v[8:9] op_sel_hi:[1,1,0]
	v_pk_mul_f32 v[2:3], v[2:3], v[6:7]
	v_addc_co_u32_e32 v11, vcc, 0, v89, vcc
	v_cvt_pk_bf16_f32 v5, v4, v2
	ds_read_b64 v[6:7], v125 offset:5632
	global_store_dword v[10:11], v5, off offset:2048
	v_mov_b32_e32 v5, v130
	s_mov_b32 s0, 0x13f00000
	v_add_co_u32_e32 v8, vcc, s0, v88
	s_waitcnt lgkmcnt(0)
	v_mul_f32_e32 v14, v130, v7
	v_pk_fma_f32 v[4:5], v[4:5], v[6:7], v[14:15] op_sel_hi:[1,1,0]
	v_pk_mul_f32 v[2:3], v[2:3], v[6:7]
	v_addc_co_u32_e32 v9, vcc, 0, v89, vcc
	v_cvt_pk_bf16_f32 v5, v4, v2
	ds_read_b64 v[6:7], v125 offset:5120
	global_store_dword v[10:11], v5, off
	v_mov_b32_e32 v5, v0
	v_add_co_u32_e32 v12, vcc, 0x11901000, v12
	s_waitcnt lgkmcnt(0)
	v_mul_f32_e32 v0, v0, v7
	v_pk_fma_f32 v[4:5], v[4:5], v[6:7], v[0:1] op_sel_hi:[1,1,0]
	v_pk_mul_f32 v[2:3], v[2:3], v[6:7]
	v_mov_b32_e32 v5, v85
	v_cvt_pk_bf16_f32 v0, v4, v2
	ds_read_b64 v[6:7], v125 offset:4608
	global_store_dword v[8:9], v0, off offset:2048
	v_addc_co_u32_e32 v13, vcc, 0, v13, vcc
	s_mov_b64 s[0:1], 0
	s_waitcnt lgkmcnt(0)
	v_mul_f32_e32 v0, v85, v7
	v_pk_fma_f32 v[4:5], v[4:5], v[6:7], v[0:1] op_sel_hi:[1,1,0]
	v_pk_mul_f32 v[2:3], v[2:3], v[6:7]
	s_nop 0
	v_cvt_pk_bf16_f32 v0, v4, v2
	global_store_dword v[8:9], v0, off
	s_waitcnt lgkmcnt(0)
	v_mov_b32_e32 v3, v4
	global_store_dwordx2 v[12:13], v[2:3], off
